# v21 plus: stepped lgkmcnt(7/5/3/1/0) waits between MFMA pairs at the heads of the two heavy MFMA segments (instead of lgkmcnt(0) before the first MFMA)
# speedup vs baseline: 1.0049x; 1.0049x over previous
; #define PG8_STAGE(bufoff, gbase, voff) do { _Pragma("unroll") for (int _i = 0; _i < 2; ++_i) \
;         __builtin_amdgcn_global_load_lds((const unsigned*)((const char*)(gbase) + (voff)[_i]), (LAS unsigned*)(lds + (bufoff) + ldsw + _i * 8192), 16, 0, 0); } while (0)
; #define PG8_LDA(dst, b, h) do { _Pragma("unroll") for (int m = 0; m < 4; ++m) _Pragma("unroll") for (int k = 0; k < 2; ++k) dst[m][k] = *(const LAS bf16x8*)(lds + PG8_SA(b, h) + aoff + m * 2048 + k * 1024); } while (0)
; #define PG8_LDB(dst, b, h) do { _Pragma("unroll") for (int n = 0; n < 2; ++n) _Pragma("unroll") for (int k = 0; k < 2; ++k) dst[n][k] = *(const LAS bf16x8*)(lds + PG8_SB(b, h) + boff + n * 2048 + k * 1024); } while (0)
; #define PG8_MMA(ai, bj, At, Bt) do { __builtin_amdgcn_s_setprio(1); _Pragma("unroll") for (int m = 0; m < 4; ++m) _Pragma("unroll") for (int n = 0; n < 2; ++n) _Pragma("unroll") for (int k = 0; k < 2; ++k) \
;         acc[ai][bj][m][n] = __builtin_amdgcn_mfma_f32_16x16x32_bf16(Bt[n][k], At[m][k], acc[ai][bj][m][n], 0, 0, 0); __builtin_amdgcn_s_setprio(0); } while (0)
; #define PG8_WAIT_V(n) asm volatile("s_waitcnt vmcnt(" #n ")" ::: "memory")
; #define PG8_WAIT_L(n) asm volatile("s_waitcnt lgkmcnt(" #n ")" ::: "memory")
; #define PG8_BAR __builtin_amdgcn_s_barrier()
; template <class Epi, class Sched>
; __device__ __forceinline__ void gemm_phase(LAS unsigned char* lds, const Gemm g, const Sched& S, const Epi& E) {
;     ...
;             const bool last = (t == nt - 2);
;             const char* a1 = cA + (size_t)(t + 1) * kstep;
;             const char* a2 = last ? nA : cA + (size_t)(t + 2) * kstep; const char* b2 = last ? nB : cB + (size_t)(t + 2) * kstep;
;             const char* a3 = a2 + kstep; const char* b3 = b2 + kstep;
;             PG8_LDB(B0, 0, 0); PG8_SCHED; PG8_LDA(At, 0, 0); PG8_STAGE(PG8_SA(1, 1), a1 + hstep, voffA);
;             PG8_WAIT_L(8); PG8_BAR; PG8_WAIT_L(0); PG8_MMA(0, 0, At, B0); PG8_BAR; PG8_SCHED;
;             PG8_LDB(B1, 0, 1); PG8_STAGE(PG8_SB(0, 0), b2, voffB);
;             PG8_BAR; PG8_WAIT_L(0); PG8_MMA(0, 1, At, B1); PG8_BAR;
;             PG8_LDA(At, 0, 1); PG8_STAGE(PG8_SA(0, 0), a2, voffA);
;             PG8_BAR; PG8_WAIT_L(0); PG8_MMA(1, 0, At, B0); PG8_BAR; PG8_SCHED;
;             PG8_STAGE(PG8_SB(0, 1), b2 + hstep, voffB);
;             PG8_WAIT_V(6); PG8_BAR; PG8_MMA(1, 1, At, B1); PG8_BAR;
.LBB0_125:
	s_add_u32 s20, s16, 0xfff80080
	s_addc_u32 s21, s17, -1
	s_add_i32 s45, 0, 0x10000
	ds_read_b128 v[138:141], v129
	ds_read_b128 v[160:163], v129 offset:1024
	ds_read_b128 v[164:167], v129 offset:2048
	ds_read_b128 v[168:171], v129 offset:3072
	s_cmp_eq_u32 s44, 28
	s_cselect_b32 s23, s7, s21
	s_cselect_b32 s22, s40, s20
	s_cselect_b32 s21, s5, s43
	s_cselect_b32 s20, s41, s42
	s_add_i32 m0, s30, 0xc000
	ds_read_b128 v[172:175], v145
	ds_read_b128 v[200:203], v145 offset:1024
	ds_read_b128 v[204:207], v145 offset:2048
	ds_read_b128 v[208:211], v145 offset:3072
	ds_read_b128 v[212:215], v145 offset:4096
	ds_read_b128 v[216:219], v145 offset:5120
	ds_read_b128 v[220:223], v145 offset:6144
	ds_read_b128 v[224:227], v145 offset:7168
	global_load_lds_dwordx4 v134, s[16:17]
	s_add_i32 m0, s30, 0xe000
	s_nop 0
	global_load_lds_dwordx4 v136, s[16:17]
	s_waitcnt lgkmcnt(8)
	s_barrier
	s_waitcnt lgkmcnt(7)
	v_mfma_f32_16x16x32_bf16 v[124:127], v[138:141], v[172:175], v[124:127]
	v_mfma_f32_16x16x32_bf16 v[120:123], v[164:167], v[172:175], v[120:123]
	s_waitcnt lgkmcnt(5)
	v_mfma_f32_16x16x32_bf16 v[116:119], v[138:141], v[204:207], v[116:119]
	v_mfma_f32_16x16x32_bf16 v[108:111], v[164:167], v[204:207], v[108:111]
	s_waitcnt lgkmcnt(3)
	v_mfma_f32_16x16x32_bf16 v[100:103], v[138:141], v[212:215], v[100:103]
	v_mfma_f32_16x16x32_bf16 v[92:95], v[164:167], v[212:215], v[92:95]
	s_waitcnt lgkmcnt(1)
	v_mfma_f32_16x16x32_bf16 v[84:87], v[138:141], v[220:223], v[84:87]
	v_mfma_f32_16x16x32_bf16 v[76:79], v[164:167], v[220:223], v[76:79]
	v_mfma_f32_16x16x32_bf16 v[124:127], v[160:163], v[200:203], v[124:127]
	v_mfma_f32_16x16x32_bf16 v[120:123], v[168:171], v[200:203], v[120:123]
	v_mfma_f32_16x16x32_bf16 v[116:119], v[160:163], v[208:211], v[116:119]
	v_mfma_f32_16x16x32_bf16 v[108:111], v[168:171], v[208:211], v[108:111]
	v_mfma_f32_16x16x32_bf16 v[100:103], v[160:163], v[216:219], v[100:103]
	v_mfma_f32_16x16x32_bf16 v[92:95], v[168:171], v[216:219], v[92:95]
	s_waitcnt lgkmcnt(0)
	v_mfma_f32_16x16x32_bf16 v[84:87], v[160:163], v[224:227], v[84:87]
	v_mfma_f32_16x16x32_bf16 v[76:79], v[168:171], v[224:227], v[76:79]
	s_barrier
	s_add_i32 s48, 0, 0x14000
	s_add_i32 s45, s45, s29
	ds_read_b128 v[228:231], v129 offset:16384
	ds_read_b128 v[232:235], v129 offset:17408
	ds_read_b128 v[236:239], v129 offset:18432
	ds_read_b128 v[240:243], v129 offset:19456
	s_add_u32 s84, s20, 0x80
	s_addc_u32 s85, s21, 0
	s_mov_b32 m0, s45
	s_nop 0
	global_load_lds_dwordx4 v148, s[20:21]
	s_add_i32 m0, s45, 0x2000
	s_nop 0
	global_load_lds_dwordx4 v128, s[20:21]
	s_barrier
	s_waitcnt lgkmcnt(0)
	v_mfma_f32_16x16x32_bf16 v[112:115], v[228:231], v[172:175], v[112:115]
	v_mfma_f32_16x16x32_bf16 v[104:107], v[236:239], v[172:175], v[104:107]
	v_mfma_f32_16x16x32_bf16 v[96:99], v[228:231], v[204:207], v[96:99]
	v_mfma_f32_16x16x32_bf16 v[88:91], v[236:239], v[204:207], v[88:91]
	v_mfma_f32_16x16x32_bf16 v[80:83], v[228:231], v[212:215], v[80:83]
	v_mfma_f32_16x16x32_bf16 v[72:75], v[236:239], v[212:215], v[72:75]
	v_mfma_f32_16x16x32_bf16 v[68:71], v[228:231], v[220:223], v[68:71]
	v_mfma_f32_16x16x32_bf16 v[64:67], v[236:239], v[220:223], v[64:67]
	v_mfma_f32_16x16x32_bf16 v[112:115], v[232:235], v[200:203], v[112:115]
	v_mfma_f32_16x16x32_bf16 v[104:107], v[240:243], v[200:203], v[104:107]
	v_mfma_f32_16x16x32_bf16 v[96:99], v[232:235], v[208:211], v[96:99]
	v_mfma_f32_16x16x32_bf16 v[88:91], v[240:243], v[208:211], v[88:91]
	v_mfma_f32_16x16x32_bf16 v[80:83], v[232:235], v[216:219], v[80:83]
	v_mfma_f32_16x16x32_bf16 v[72:75], v[240:243], v[216:219], v[72:75]
	v_mfma_f32_16x16x32_bf16 v[68:71], v[232:235], v[224:227], v[68:71]
	v_mfma_f32_16x16x32_bf16 v[64:67], v[240:243], v[224:227], v[64:67]
	s_barrier
	s_mov_b32 m0, s30
	s_add_u32 s86, s22, 0x80
	s_addc_u32 s87, s23, 0
	ds_read_b128 v[172:175], v145 offset:16384
	ds_read_b128 v[200:203], v145 offset:17408
	ds_read_b128 v[204:207], v145 offset:18432
	ds_read_b128 v[208:211], v145 offset:19456
	ds_read_b128 v[212:215], v145 offset:20480
	ds_read_b128 v[216:219], v145 offset:21504
	ds_read_b128 v[220:223], v145 offset:22528
	ds_read_b128 v[224:227], v145 offset:23552
	global_load_lds_dwordx4 v132, s[22:23]
	s_mov_b32 m0, s31
	s_nop 0
	global_load_lds_dwordx4 v130, s[22:23]
	s_barrier
	s_waitcnt lgkmcnt(0)
	v_mfma_f32_16x16x32_bf16 v[60:63], v[138:141], v[172:175], v[60:63]
	v_mfma_f32_16x16x32_bf16 v[56:59], v[164:167], v[172:175], v[56:59]
	v_mfma_f32_16x16x32_bf16 v[52:55], v[138:141], v[204:207], v[52:55]
	v_mfma_f32_16x16x32_bf16 v[44:47], v[164:167], v[204:207], v[44:47]
	v_mfma_f32_16x16x32_bf16 v[36:39], v[138:141], v[212:215], v[36:39]
	v_mfma_f32_16x16x32_bf16 v[28:31], v[164:167], v[212:215], v[28:31]
	v_mfma_f32_16x16x32_bf16 v[20:23], v[138:141], v[220:223], v[20:23]
	v_mfma_f32_16x16x32_bf16 v[12:15], v[164:167], v[220:223], v[12:15]
	v_mfma_f32_16x16x32_bf16 v[60:63], v[160:163], v[200:203], v[60:63]
	v_mfma_f32_16x16x32_bf16 v[56:59], v[168:171], v[200:203], v[56:59]
	v_mfma_f32_16x16x32_bf16 v[52:55], v[160:163], v[208:211], v[52:55]
	v_mfma_f32_16x16x32_bf16 v[44:47], v[168:171], v[208:211], v[44:47]
	v_mfma_f32_16x16x32_bf16 v[36:39], v[160:163], v[216:219], v[36:39]
	v_mfma_f32_16x16x32_bf16 v[28:31], v[168:171], v[216:219], v[28:31]
	v_mfma_f32_16x16x32_bf16 v[20:23], v[160:163], v[224:227], v[20:23]
	v_mfma_f32_16x16x32_bf16 v[12:15], v[168:171], v[224:227], v[12:15]
	s_barrier
	s_add_u32 s46, s20, 0x80000
	s_addc_u32 s47, s21, 0
	s_add_i32 s45, s48, s29
	s_mov_b32 m0, s45
	s_nop 0
	global_load_lds_dwordx4 v148, s[46:47]
	s_add_i32 m0, s45, 0x2000
	s_nop 0
	global_load_lds_dwordx4 v128, s[46:47]
	s_waitcnt vmcnt(6)
	s_barrier
; #define PG8_STAGE(bufoff, gbase, voff) do { _Pragma("unroll") for (int _i = 0; _i < 2; ++_i) \
;         __builtin_amdgcn_global_load_lds((const unsigned*)((const char*)(gbase) + (voff)[_i]), (LAS unsigned*)(lds + (bufoff) + ldsw + _i * 8192), 16, 0, 0); } while (0)
; #define PG8_LDA(dst, b, h) do { _Pragma("unroll") for (int m = 0; m < 4; ++m) _Pragma("unroll") for (int k = 0; k < 2; ++k) dst[m][k] = *(const LAS bf16x8*)(lds + PG8_SA(b, h) + aoff + m * 2048 + k * 1024); } while (0)
; #define PG8_LDB(dst, b, h) do { _Pragma("unroll") for (int n = 0; n < 2; ++n) _Pragma("unroll") for (int k = 0; k < 2; ++k) dst[n][k] = *(const LAS bf16x8*)(lds + PG8_SB(b, h) + boff + n * 2048 + k * 1024); } while (0)
; #define PG8_MMA(ai, bj, At, Bt) do { __builtin_amdgcn_s_setprio(1); _Pragma("unroll") for (int m = 0; m < 4; ++m) _Pragma("unroll") for (int n = 0; n < 2; ++n) _Pragma("unroll") for (int k = 0; k < 2; ++k) \
;         acc[ai][bj][m][n] = __builtin_amdgcn_mfma_f32_16x16x32_bf16(Bt[n][k], At[m][k], acc[ai][bj][m][n], 0, 0, 0); __builtin_amdgcn_s_setprio(0); } while (0)
; #define PG8_WAIT_V(n) asm volatile("s_waitcnt vmcnt(" #n ")" ::: "memory")
; #define PG8_WAIT_L(n) asm volatile("s_waitcnt lgkmcnt(" #n ")" ::: "memory")
; #define PG8_BAR __builtin_amdgcn_s_barrier()
; #define PG8_SCHED __builtin_amdgcn_sched_barrier(0)
; template <class Epi, class Sched>
; __device__ __forceinline__ void gemm_phase(LAS unsigned char* lds, const Gemm g, const Sched& S, const Epi& E) {
;     ...
;             PG8_WAIT_V(6); PG8_BAR; PG8_MMA(1, 1, At, B1); PG8_BAR;
;             PG8_LDB(B0, 1, 0); PG8_SCHED; PG8_LDA(At, 1, 0); PG8_STAGE(PG8_SA(0, 1), a2 + hstep, voffA);
;             PG8_WAIT_L(8); PG8_BAR; PG8_WAIT_L(0); PG8_MMA(0, 0, At, B0); PG8_BAR; PG8_SCHED;
;             PG8_LDB(B1, 1, 1); PG8_STAGE(PG8_SB(1, 0), b3, voffB);
;             PG8_BAR; PG8_WAIT_L(0); PG8_MMA(0, 1, At, B1); PG8_BAR;
;             PG8_LDA(At, 1, 1); PG8_STAGE(PG8_SA(1, 0), a3, voffA);
;             PG8_BAR; PG8_WAIT_L(0); PG8_MMA(1, 0, At, B0); PG8_BAR; PG8_SCHED;
	v_mfma_f32_16x16x32_bf16 v[48:51], v[228:231], v[172:175], v[48:51]
	v_mfma_f32_16x16x32_bf16 v[40:43], v[236:239], v[172:175], v[40:43]
	v_mfma_f32_16x16x32_bf16 v[32:35], v[228:231], v[204:207], v[32:35]
	v_mfma_f32_16x16x32_bf16 v[24:27], v[236:239], v[204:207], v[24:27]
	v_mfma_f32_16x16x32_bf16 v[16:19], v[228:231], v[212:215], v[16:19]
	v_mfma_f32_16x16x32_bf16 v[8:11], v[236:239], v[212:215], v[8:11]
	v_mfma_f32_16x16x32_bf16 v[4:7], v[228:231], v[220:223], v[4:7]
	v_mfma_f32_16x16x32_bf16 v[0:3], v[236:239], v[220:223], v[0:3]
	v_mfma_f32_16x16x32_bf16 v[48:51], v[232:235], v[200:203], v[48:51]
	v_mfma_f32_16x16x32_bf16 v[40:43], v[240:243], v[200:203], v[40:43]
	v_mfma_f32_16x16x32_bf16 v[32:35], v[232:235], v[208:211], v[32:35]
	v_mfma_f32_16x16x32_bf16 v[24:27], v[240:243], v[208:211], v[24:27]
	v_mfma_f32_16x16x32_bf16 v[16:19], v[232:235], v[216:219], v[16:19]
	v_mfma_f32_16x16x32_bf16 v[8:11], v[240:243], v[216:219], v[8:11]
	v_mfma_f32_16x16x32_bf16 v[4:7], v[232:235], v[224:227], v[4:7]
	v_mfma_f32_16x16x32_bf16 v[0:3], v[240:243], v[224:227], v[0:3]
	s_barrier
	s_add_i32 s45, 0, 0x18000
	ds_read_b128 v[138:141], v129 offset:32768
	ds_read_b128 v[160:163], v129 offset:33792
	ds_read_b128 v[164:167], v129 offset:34816
	ds_read_b128 v[168:171], v129 offset:35840
	s_add_u32 s22, s22, 0x80000
	s_addc_u32 s23, s23, 0
	s_mov_b32 m0, s33
	ds_read_b128 v[172:175], v145 offset:32768
	ds_read_b128 v[200:203], v145 offset:33792
	ds_read_b128 v[204:207], v145 offset:34816
	ds_read_b128 v[208:211], v145 offset:35840
	ds_read_b128 v[212:215], v145 offset:36864
	ds_read_b128 v[216:219], v145 offset:37888
	ds_read_b128 v[220:223], v145 offset:38912
	ds_read_b128 v[224:227], v145 offset:39936
	global_load_lds_dwordx4 v132, s[22:23]
	s_mov_b32 m0, s34
	s_nop 0
	global_load_lds_dwordx4 v130, s[22:23]
	s_waitcnt lgkmcnt(8)
	s_barrier
	s_waitcnt lgkmcnt(7)
	v_mfma_f32_16x16x32_bf16 v[124:127], v[138:141], v[172:175], v[124:127]
	v_mfma_f32_16x16x32_bf16 v[120:123], v[164:167], v[172:175], v[120:123]
	s_waitcnt lgkmcnt(5)
	v_mfma_f32_16x16x32_bf16 v[116:119], v[138:141], v[204:207], v[116:119]
	v_mfma_f32_16x16x32_bf16 v[108:111], v[164:167], v[204:207], v[108:111]
	s_waitcnt lgkmcnt(3)
	v_mfma_f32_16x16x32_bf16 v[100:103], v[138:141], v[212:215], v[100:103]
	v_mfma_f32_16x16x32_bf16 v[92:95], v[164:167], v[212:215], v[92:95]
	s_waitcnt lgkmcnt(1)
	v_mfma_f32_16x16x32_bf16 v[84:87], v[138:141], v[220:223], v[84:87]
	v_mfma_f32_16x16x32_bf16 v[76:79], v[164:167], v[220:223], v[76:79]
	v_mfma_f32_16x16x32_bf16 v[124:127], v[160:163], v[200:203], v[124:127]
	v_mfma_f32_16x16x32_bf16 v[120:123], v[168:171], v[200:203], v[120:123]
	v_mfma_f32_16x16x32_bf16 v[116:119], v[160:163], v[208:211], v[116:119]
	v_mfma_f32_16x16x32_bf16 v[108:111], v[168:171], v[208:211], v[108:111]
	v_mfma_f32_16x16x32_bf16 v[100:103], v[160:163], v[216:219], v[100:103]
	v_mfma_f32_16x16x32_bf16 v[92:95], v[168:171], v[216:219], v[92:95]
	s_waitcnt lgkmcnt(0)
	v_mfma_f32_16x16x32_bf16 v[84:87], v[160:163], v[224:227], v[84:87]
	v_mfma_f32_16x16x32_bf16 v[76:79], v[168:171], v[224:227], v[76:79]
	s_barrier
	s_add_i32 s22, 0, 0x1c000
	s_add_i32 s23, s45, s29
	s_mov_b32 m0, s23
	ds_read_b128 v[228:231], v129 offset:49152
	ds_read_b128 v[232:235], v129 offset:50176
	ds_read_b128 v[236:239], v129 offset:51200
	ds_read_b128 v[240:243], v129 offset:52224
	global_load_lds_dwordx4 v148, s[84:85]
	s_add_i32 m0, s23, 0x2000
	s_nop 0
	global_load_lds_dwordx4 v128, s[84:85]
	s_barrier
	s_waitcnt lgkmcnt(0)
	v_mfma_f32_16x16x32_bf16 v[112:115], v[228:231], v[172:175], v[112:115]
	v_mfma_f32_16x16x32_bf16 v[104:107], v[236:239], v[172:175], v[104:107]
	v_mfma_f32_16x16x32_bf16 v[96:99], v[228:231], v[204:207], v[96:99]
	v_mfma_f32_16x16x32_bf16 v[88:91], v[236:239], v[204:207], v[88:91]
	v_mfma_f32_16x16x32_bf16 v[80:83], v[228:231], v[212:215], v[80:83]
	v_mfma_f32_16x16x32_bf16 v[72:75], v[236:239], v[212:215], v[72:75]
	v_mfma_f32_16x16x32_bf16 v[68:71], v[228:231], v[220:223], v[68:71]
	v_mfma_f32_16x16x32_bf16 v[64:67], v[236:239], v[220:223], v[64:67]
	v_mfma_f32_16x16x32_bf16 v[112:115], v[232:235], v[200:203], v[112:115]
	v_mfma_f32_16x16x32_bf16 v[104:107], v[240:243], v[200:203], v[104:107]
	v_mfma_f32_16x16x32_bf16 v[96:99], v[232:235], v[208:211], v[96:99]
	v_mfma_f32_16x16x32_bf16 v[88:91], v[240:243], v[208:211], v[88:91]
	v_mfma_f32_16x16x32_bf16 v[80:83], v[232:235], v[216:219], v[80:83]
	v_mfma_f32_16x16x32_bf16 v[72:75], v[240:243], v[216:219], v[72:75]
	v_mfma_f32_16x16x32_bf16 v[68:71], v[232:235], v[224:227], v[68:71]
	v_mfma_f32_16x16x32_bf16 v[64:67], v[240:243], v[224:227], v[64:67]
	s_barrier
	s_mov_b32 m0, s35
	ds_read_b128 v[172:175], v145 offset:49152
	ds_read_b128 v[200:203], v145 offset:50176
	ds_read_b128 v[204:207], v145 offset:51200
	ds_read_b128 v[208:211], v145 offset:52224
	ds_read_b128 v[212:215], v145 offset:53248
	ds_read_b128 v[216:219], v145 offset:54272
	ds_read_b128 v[220:223], v145 offset:55296
	ds_read_b128 v[224:227], v145 offset:56320
	global_load_lds_dwordx4 v132, s[86:87]
	s_mov_b32 m0, s36
	s_nop 0
	global_load_lds_dwordx4 v130, s[86:87]
	s_barrier
; #define PG8_STAGE(bufoff, gbase, voff) do { _Pragma("unroll") for (int _i = 0; _i < 2; ++_i) \
;         __builtin_amdgcn_global_load_lds((const unsigned*)((const char*)(gbase) + (voff)[_i]), (LAS unsigned*)(lds + (bufoff) + ldsw + _i * 8192), 16, 0, 0); } while (0)
; #define PG8_MMA(ai, bj, At, Bt) do { __builtin_amdgcn_s_setprio(1); _Pragma("unroll") for (int m = 0; m < 4; ++m) _Pragma("unroll") for (int n = 0; n < 2; ++n) _Pragma("unroll") for (int k = 0; k < 2; ++k) \
;         acc[ai][bj][m][n] = __builtin_amdgcn_mfma_f32_16x16x32_bf16(Bt[n][k], At[m][k], acc[ai][bj][m][n], 0, 0, 0); __builtin_amdgcn_s_setprio(0); } while (0)
; #define PG8_WAIT_V(n) asm volatile("s_waitcnt vmcnt(" #n ")" ::: "memory")
; #define PG8_WAIT_L(n) asm volatile("s_waitcnt lgkmcnt(" #n ")" ::: "memory")
; #define PG8_BAR __builtin_amdgcn_s_barrier()
; #define PG8_SCHED __builtin_amdgcn_sched_barrier(0)
; template <class Epi, class Sched>
; __device__ __forceinline__ void gemm_phase(LAS unsigned char* lds, const Gemm g, const Sched& S, const Epi& E) {
;     ...
;             PG8_BAR; PG8_WAIT_L(0); PG8_MMA(1, 0, At, B0); PG8_BAR; PG8_SCHED;
;             PG8_STAGE(PG8_SB(1, 1), b3 + hstep, voffB);
;             PG8_WAIT_V(6); PG8_BAR; PG8_MMA(1, 1, At, B1); PG8_BAR;
	s_waitcnt lgkmcnt(0)
	v_mfma_f32_16x16x32_bf16 v[60:63], v[138:141], v[172:175], v[60:63]
	v_mfma_f32_16x16x32_bf16 v[56:59], v[164:167], v[172:175], v[56:59]
	v_mfma_f32_16x16x32_bf16 v[52:55], v[138:141], v[204:207], v[52:55]
	v_mfma_f32_16x16x32_bf16 v[44:47], v[164:167], v[204:207], v[44:47]
	v_mfma_f32_16x16x32_bf16 v[36:39], v[138:141], v[212:215], v[36:39]
	v_mfma_f32_16x16x32_bf16 v[28:31], v[164:167], v[212:215], v[28:31]
	v_mfma_f32_16x16x32_bf16 v[20:23], v[138:141], v[220:223], v[20:23]
	v_mfma_f32_16x16x32_bf16 v[12:15], v[164:167], v[220:223], v[12:15]
	v_mfma_f32_16x16x32_bf16 v[60:63], v[160:163], v[200:203], v[60:63]
	v_mfma_f32_16x16x32_bf16 v[56:59], v[168:171], v[200:203], v[56:59]
	v_mfma_f32_16x16x32_bf16 v[52:55], v[160:163], v[208:211], v[52:55]
	v_mfma_f32_16x16x32_bf16 v[44:47], v[168:171], v[208:211], v[44:47]
	v_mfma_f32_16x16x32_bf16 v[36:39], v[160:163], v[216:219], v[36:39]
	v_mfma_f32_16x16x32_bf16 v[28:31], v[168:171], v[216:219], v[28:31]
	v_mfma_f32_16x16x32_bf16 v[20:23], v[160:163], v[224:227], v[20:23]
	v_mfma_f32_16x16x32_bf16 v[12:15], v[168:171], v[224:227], v[12:15]
	s_barrier
	s_add_u32 s20, s20, 0x80080
	s_addc_u32 s21, s21, 0
	s_add_i32 s22, s22, s29
	s_mov_b32 m0, s22
	s_nop 0
	global_load_lds_dwordx4 v148, s[20:21]
	s_add_i32 m0, s22, 0x2000
	s_nop 0
	global_load_lds_dwordx4 v128, s[20:21]
	s_add_i32 s44, s44, 2
	s_add_u32 s16, s16, 0x100
	s_addc_u32 s17, s17, 0
	s_add_u32 s42, s42, 0x100
	s_addc_u32 s43, s43, 0
	s_cmp_gt_u32 s44, 29
	s_waitcnt vmcnt(6)
	s_barrier
	v_mfma_f32_16x16x32_bf16 v[48:51], v[228:231], v[172:175], v[48:51]
	v_mfma_f32_16x16x32_bf16 v[40:43], v[236:239], v[172:175], v[40:43]
	v_mfma_f32_16x16x32_bf16 v[32:35], v[228:231], v[204:207], v[32:35]
	v_mfma_f32_16x16x32_bf16 v[24:27], v[236:239], v[204:207], v[24:27]
	v_mfma_f32_16x16x32_bf16 v[16:19], v[228:231], v[212:215], v[16:19]
	v_mfma_f32_16x16x32_bf16 v[8:11], v[236:239], v[212:215], v[8:11]
	v_mfma_f32_16x16x32_bf16 v[4:7], v[228:231], v[220:223], v[4:7]
	v_mfma_f32_16x16x32_bf16 v[0:3], v[236:239], v[220:223], v[0:3]
	v_mfma_f32_16x16x32_bf16 v[48:51], v[232:235], v[200:203], v[48:51]
	v_mfma_f32_16x16x32_bf16 v[40:43], v[240:243], v[200:203], v[40:43]
	v_mfma_f32_16x16x32_bf16 v[32:35], v[232:235], v[208:211], v[32:35]
	v_mfma_f32_16x16x32_bf16 v[24:27], v[240:243], v[208:211], v[24:27]
	v_mfma_f32_16x16x32_bf16 v[16:19], v[232:235], v[216:219], v[16:19]
	v_mfma_f32_16x16x32_bf16 v[8:11], v[240:243], v[216:219], v[8:11]
	v_mfma_f32_16x16x32_bf16 v[4:7], v[232:235], v[224:227], v[4:7]
	v_mfma_f32_16x16x32_bf16 v[0:3], v[240:243], v[224:227], v[0:3]
	s_barrier
	s_cbranch_scc0 .LBB0_125
; __device__ __forceinline__ unsigned cvt_pk_bf16(float lo, float hi) { unsigned r; asm("v_cvt_pk_bf16_f32 %0, %1, %2" : "=v"(r) : "v"(lo), "v"(hi)); return r; }
;     __device__ __forceinline__ void operator()(const f32x4 (&acc)[2][2][4][2], const Unit& u, int wr, int wc, int fr, int fq) const {
;         const int row0 = u.pm * BM + wr * 64 + fr, col0 = u.pn * BM + wc * 32 + 8 * fq;
; #pragma unroll
;         for (int ai = 0; ai < 2; ++ai)
; #pragma unroll
;             for (int m = 0; m < 4; ++m) { bf16_t* rowp = O + (size_t)(row0 + ai * HALF + m * 16) * ldc + col0;
; #pragma unroll
;                 for (int bj = 0; bj < 2; ++bj) { const f32x4 v0 = acc[ai][bj][m][0], v1 = acc[ai][bj][m][1];
;                     u32x4 w; w.x = cvt_pk_bf16(v0[0], v0[1]); w.y = cvt_pk_bf16(v0[2], v0[3]); w.z = cvt_pk_bf16(v1[0], v1[1]); w.w = cvt_pk_bf16(v1[2], v1[3]);
;                     *(u32x4*)(rowp + bj * HALF) = w; } }
	v_lshl_add_u32 v160, s39, 8, v142
	v_lshl_or_b32 v140, s38, 8, v144
	v_ashrrev_i32_e32 v141, 31, v140
	v_mov_b64_e32 v[138:139], s[2:3]
	v_cvt_pk_bf16_f32 v68, v68, v69
	v_cvt_pk_bf16_f32 v69, v70, v71
	v_cvt_pk_bf16_f32 v70, v64, v65
	v_add_u32_e32 v64, 0x80, v160
	v_mad_i64_i32 v[146:147], s[16:17], v160, s56, v[138:139]
	v_lshlrev_b64 v[140:141], 1, v[140:141]
	v_cvt_pk_bf16_f32 v112, v112, v113
	v_cvt_pk_bf16_f32 v113, v114, v115
	v_cvt_pk_bf16_f32 v114, v104, v105
	v_or_b32_e32 v104, 16, v160
	v_mad_i64_i32 v[64:65], s[16:17], v64, s56, v[138:139]
	v_cvt_pk_bf16_f32 v48, v48, v49
	v_cvt_pk_bf16_f32 v49, v50, v51
	v_cvt_pk_bf16_f32 v50, v40, v41
	v_add_u32_e32 v40, 0x90, v160
	v_lshl_add_u64 v[146:147], v[146:147], 0, v[140:141]
	v_mad_i64_i32 v[104:105], s[16:17], v104, s56, v[138:139]
	v_cvt_pk_bf16_f32 v96, v96, v97
	v_cvt_pk_bf16_f32 v97, v98, v99
	v_cvt_pk_bf16_f32 v98, v88, v89
	v_or_b32_e32 v88, 32, v160
	v_lshl_add_u64 v[64:65], v[64:65], 0, v[140:141]
	v_mad_i64_i32 v[40:41], s[16:17], v40, s56, v[138:139]
	v_cvt_pk_bf16_f32 v32, v32, v33
	v_cvt_pk_bf16_f32 v33, v34, v35
	v_cvt_pk_bf16_f32 v34, v24, v25
	v_add_u32_e32 v24, 0xa0, v160
	v_cvt_pk_bf16_f32 v115, v106, v107
	global_store_dwordx4 v[146:147], v[112:115], off offset:256
	v_mad_i64_i32 v[88:89], s[16:17], v88, s56, v[138:139]
	s_nop 0
	v_lshl_add_u64 v[112:113], v[104:105], 0, v[140:141]
	v_cvt_pk_bf16_f32 v80, v80, v81
	v_cvt_pk_bf16_f32 v81, v82, v83
	v_cvt_pk_bf16_f32 v82, v72, v73
	v_or_b32_e32 v72, 48, v160
	v_cvt_pk_bf16_f32 v51, v42, v43
	global_store_dwordx4 v[64:65], v[48:51], off offset:256
	v_mad_i64_i32 v[24:25], s[16:17], v24, s56, v[138:139]
	s_nop 0
	v_lshl_add_u64 v[48:49], v[40:41], 0, v[140:141]
	v_cvt_pk_bf16_f32 v16, v16, v17
	v_cvt_pk_bf16_f32 v17, v18, v19
	v_cvt_pk_bf16_f32 v18, v8, v9
	v_add_u32_e32 v8, 0xb0, v160
	v_cvt_pk_bf16_f32 v99, v90, v91
	global_store_dwordx4 v[112:113], v[96:99], off offset:256
	v_mad_i64_i32 v[72:73], s[16:17], v72, s56, v[138:139]
	s_nop 0
	v_lshl_add_u64 v[96:97], v[88:89], 0, v[140:141]
	v_cvt_pk_bf16_f32 v35, v26, v27
	global_store_dwordx4 v[48:49], v[32:35], off offset:256
	v_mad_i64_i32 v[8:9], s[16:17], v8, s56, v[138:139]
	s_nop 0
	v_lshl_add_u64 v[32:33], v[24:25], 0, v[140:141]
	v_cvt_pk_bf16_f32 v83, v74, v75
	global_store_dwordx4 v[96:97], v[80:83], off offset:256
	v_cvt_pk_bf16_f32 v19, v10, v11
	global_store_dwordx4 v[32:33], v[16:19], off offset:256
	s_and_b64 vcc, exec, s[0:1]
	v_lshl_add_u64 v[80:81], v[72:73], 0, v[140:141]
	v_lshl_add_u64 v[16:17], v[8:9], 0, v[140:141]
	s_mov_b32 s38, s4
	s_mov_b32 s39, s6
	s_mov_b64 s[20:21], s[14:15]
	s_mov_b64 s[16:17], s[12:13]
	v_cvt_pk_bf16_f32 v124, v124, v125
	v_cvt_pk_bf16_f32 v125, v126, v127
	v_cvt_pk_bf16_f32 v126, v120, v121
	v_cvt_pk_bf16_f32 v127, v122, v123
	global_store_dwordx4 v[146:147], v[124:127], off
	v_cvt_pk_bf16_f32 v104, v116, v117
	v_cvt_pk_bf16_f32 v105, v118, v119
	v_cvt_pk_bf16_f32 v106, v108, v109
	v_cvt_pk_bf16_f32 v107, v110, v111
	global_store_dwordx4 v[112:113], v[104:107], off
	v_cvt_pk_bf16_f32 v88, v100, v101
	v_cvt_pk_bf16_f32 v89, v102, v103
	v_cvt_pk_bf16_f32 v90, v92, v93
	v_cvt_pk_bf16_f32 v91, v94, v95
	global_store_dwordx4 v[96:97], v[88:91], off
	v_cvt_pk_bf16_f32 v72, v84, v85
	v_cvt_pk_bf16_f32 v73, v86, v87
	v_cvt_pk_bf16_f32 v74, v76, v77
	v_cvt_pk_bf16_f32 v75, v78, v79
	global_store_dwordx4 v[80:81], v[72:75], off
	v_cvt_pk_bf16_f32 v71, v66, v67
	global_store_dwordx4 v[80:81], v[68:71], off offset:256
	v_cvt_pk_bf16_f32 v60, v60, v61
	v_cvt_pk_bf16_f32 v61, v62, v63
	v_cvt_pk_bf16_f32 v62, v56, v57
	v_cvt_pk_bf16_f32 v63, v58, v59
	global_store_dwordx4 v[64:65], v[60:63], off
	v_cvt_pk_bf16_f32 v40, v52, v53
	v_cvt_pk_bf16_f32 v41, v54, v55
	v_cvt_pk_bf16_f32 v42, v44, v45
	v_cvt_pk_bf16_f32 v43, v46, v47
	global_store_dwordx4 v[48:49], v[40:43], off
	v_cvt_pk_bf16_f32 v24, v36, v37
	v_cvt_pk_bf16_f32 v25, v38, v39
	v_cvt_pk_bf16_f32 v26, v28, v29
	v_cvt_pk_bf16_f32 v27, v30, v31
	global_store_dwordx4 v[32:33], v[24:27], off
	v_cvt_pk_bf16_f32 v8, v20, v21
	v_cvt_pk_bf16_f32 v9, v22, v23
	v_cvt_pk_bf16_f32 v10, v12, v13
	v_cvt_pk_bf16_f32 v11, v14, v15
	global_store_dwordx4 v[16:17], v[8:11], off
	v_cvt_pk_bf16_f32 v4, v4, v5
	v_cvt_pk_bf16_f32 v5, v6, v7
	v_cvt_pk_bf16_f32 v6, v0, v1
	v_cvt_pk_bf16_f32 v7, v2, v3
	global_store_dwordx4 v[16:17], v[4:7], off offset:256
	s_cbranch_vccz .LBB0_118
	s_waitcnt vmcnt(0)
	s_cmpk_gt_u32 s24, 0xff
	s_cbranch_scc1 .LBB0_129
	s_barrier

; #define PG8_STAGE(bufoff, gbase, voff) do { _Pragma("unroll") for (int _i = 0; _i < 2; ++_i) \
;         __builtin_amdgcn_global_load_lds((const unsigned*)((const char*)(gbase) + (voff)[_i]), (LAS unsigned*)(lds + (bufoff) + ldsw + _i * 8192), 16, 0, 0); } while (0)
; #define PG8_LDA(dst, b, h) do { _Pragma("unroll") for (int m = 0; m < 4; ++m) _Pragma("unroll") for (int k = 0; k < 2; ++k) dst[m][k] = *(const LAS bf16x8*)(lds + PG8_SA(b, h) + aoff + m * 2048 + k * 1024); } while (0)
; #define PG8_LDB(dst, b, h) do { _Pragma("unroll") for (int n = 0; n < 2; ++n) _Pragma("unroll") for (int k = 0; k < 2; ++k) dst[n][k] = *(const LAS bf16x8*)(lds + PG8_SB(b, h) + boff + n * 2048 + k * 1024); } while (0)
; #define PG8_MMA(ai, bj, At, Bt) do { __builtin_amdgcn_s_setprio(1); _Pragma("unroll") for (int m = 0; m < 4; ++m) _Pragma("unroll") for (int n = 0; n < 2; ++n) _Pragma("unroll") for (int k = 0; k < 2; ++k) \
;         acc[ai][bj][m][n] = __builtin_amdgcn_mfma_f32_16x16x32_bf16(Bt[n][k], At[m][k], acc[ai][bj][m][n], 0, 0, 0); __builtin_amdgcn_s_setprio(0); } while (0)
; #define PG8_WAIT_V(n) asm volatile("s_waitcnt vmcnt(" #n ")" ::: "memory")
; #define PG8_WAIT_L(n) asm volatile("s_waitcnt lgkmcnt(" #n ")" ::: "memory")
; #define PG8_BAR __builtin_amdgcn_s_barrier()
; template <class Epi, class Sched>
; __device__ __forceinline__ void gemm_phase(LAS unsigned char* lds, const Gemm g, const Sched& S, const Epi& E) {
;     ...
;             const bool last = (t == nt - 2);
;             const char* a1 = cA + (size_t)(t + 1) * kstep;
;             const char* a2 = last ? nA : cA + (size_t)(t + 2) * kstep; const char* b2 = last ? nB : cB + (size_t)(t + 2) * kstep;
;             const char* a3 = a2 + kstep; const char* b3 = b2 + kstep;
;             PG8_LDB(B0, 0, 0); PG8_SCHED; PG8_LDA(At, 0, 0); PG8_STAGE(PG8_SA(1, 1), a1 + hstep, voffA);
;             PG8_WAIT_L(8); PG8_BAR; PG8_WAIT_L(0); PG8_MMA(0, 0, At, B0); PG8_BAR; PG8_SCHED;
;             PG8_LDB(B1, 0, 1); PG8_STAGE(PG8_SB(0, 0), b2, voffB);
;             PG8_BAR; PG8_WAIT_L(0); PG8_MMA(0, 1, At, B1); PG8_BAR;
;             PG8_LDA(At, 0, 1); PG8_STAGE(PG8_SA(0, 0), a2, voffA);
;             PG8_BAR; PG8_WAIT_L(0); PG8_MMA(1, 0, At, B0); PG8_BAR; PG8_SCHED;
;             PG8_STAGE(PG8_SB(0, 1), b2 + hstep, voffB);
;             PG8_WAIT_V(6); PG8_BAR; PG8_MMA(1, 1, At, B1); PG8_BAR;
.LBB0_170:
	s_add_i32 s53, s22, 2
	s_add_u32 s20, s16, 0x100
	s_addc_u32 s21, s17, 0
	s_add_i32 s54, 0, 0x10000
	ds_read_b128 v[128:131], v141
	ds_read_b128 v[132:135], v141 offset:1024
	ds_read_b128 v[136:139], v141 offset:2048
	ds_read_b128 v[160:163], v141 offset:3072
	s_cmp_eq_u32 s15, s22
	s_cselect_b32 s22, s4, s51
	s_cselect_b32 s25, s7, s21
	s_cselect_b32 s24, s6, s20
	s_cselect_b32 s23, s5, s52
	s_add_i32 m0, s35, 0xc000
	ds_read_b128 v[164:167], v173
	ds_read_b128 v[174:177], v173 offset:1024
	ds_read_b128 v[200:203], v173 offset:2048
	ds_read_b128 v[204:207], v173 offset:3072
	ds_read_b128 v[208:211], v173 offset:4096
	ds_read_b128 v[212:215], v173 offset:5120
	ds_read_b128 v[216:219], v173 offset:6144
	ds_read_b128 v[220:223], v173 offset:7168
	global_load_lds_dwordx4 v142, s[16:17]
	s_add_i32 m0, s35, 0xe000
	s_nop 0
	global_load_lds_dwordx4 v144, s[16:17]
	s_waitcnt lgkmcnt(8)
	s_barrier
	s_waitcnt lgkmcnt(7)
	v_mfma_f32_16x16x32_bf16 v[124:127], v[128:131], v[164:167], v[124:127]
	v_mfma_f32_16x16x32_bf16 v[120:123], v[136:139], v[164:167], v[120:123]
	s_waitcnt lgkmcnt(5)
	v_mfma_f32_16x16x32_bf16 v[116:119], v[128:131], v[200:203], v[116:119]
	v_mfma_f32_16x16x32_bf16 v[112:115], v[136:139], v[200:203], v[112:115]
	s_waitcnt lgkmcnt(3)
	v_mfma_f32_16x16x32_bf16 v[100:103], v[128:131], v[208:211], v[100:103]
	v_mfma_f32_16x16x32_bf16 v[96:99], v[136:139], v[208:211], v[96:99]
	s_waitcnt lgkmcnt(1)
	v_mfma_f32_16x16x32_bf16 v[84:87], v[128:131], v[216:219], v[84:87]
	v_mfma_f32_16x16x32_bf16 v[80:83], v[136:139], v[216:219], v[80:83]
	v_mfma_f32_16x16x32_bf16 v[124:127], v[132:135], v[174:177], v[124:127]
	v_mfma_f32_16x16x32_bf16 v[120:123], v[160:163], v[174:177], v[120:123]
	v_mfma_f32_16x16x32_bf16 v[116:119], v[132:135], v[204:207], v[116:119]
	v_mfma_f32_16x16x32_bf16 v[112:115], v[160:163], v[204:207], v[112:115]
	v_mfma_f32_16x16x32_bf16 v[100:103], v[132:135], v[212:215], v[100:103]
	v_mfma_f32_16x16x32_bf16 v[96:99], v[160:163], v[212:215], v[96:99]
	s_waitcnt lgkmcnt(0)
	v_mfma_f32_16x16x32_bf16 v[84:87], v[132:135], v[220:223], v[84:87]
	v_mfma_f32_16x16x32_bf16 v[80:83], v[160:163], v[220:223], v[80:83]
	s_barrier
	s_add_i32 s55, 0, 0x14000
	s_add_i32 s16, s54, s29
	ds_read_b128 v[224:227], v141 offset:16384
	ds_read_b128 v[228:231], v141 offset:17408
	ds_read_b128 v[232:235], v141 offset:18432
	ds_read_b128 v[236:239], v141 offset:19456
	s_add_u32 s84, s22, 0x80
	s_addc_u32 s85, s23, 0
	s_mov_b32 m0, s16
	s_nop 0
	global_load_lds_dwordx4 v148, s[22:23]
	s_add_i32 m0, s16, 0x2000
	s_nop 0
	global_load_lds_dwordx4 v140, s[22:23]
	s_barrier
	s_waitcnt lgkmcnt(0)
	v_mfma_f32_16x16x32_bf16 v[108:111], v[224:227], v[164:167], v[108:111]
	v_mfma_f32_16x16x32_bf16 v[104:107], v[232:235], v[164:167], v[104:107]
	v_mfma_f32_16x16x32_bf16 v[92:95], v[224:227], v[200:203], v[92:95]
	v_mfma_f32_16x16x32_bf16 v[88:91], v[232:235], v[200:203], v[88:91]
	v_mfma_f32_16x16x32_bf16 v[76:79], v[224:227], v[208:211], v[76:79]
	v_mfma_f32_16x16x32_bf16 v[72:75], v[232:235], v[208:211], v[72:75]
	v_mfma_f32_16x16x32_bf16 v[68:71], v[224:227], v[216:219], v[68:71]
	v_mfma_f32_16x16x32_bf16 v[64:67], v[232:235], v[216:219], v[64:67]
	v_mfma_f32_16x16x32_bf16 v[108:111], v[228:231], v[174:177], v[108:111]
	v_mfma_f32_16x16x32_bf16 v[104:107], v[236:239], v[174:177], v[104:107]
	v_mfma_f32_16x16x32_bf16 v[92:95], v[228:231], v[204:207], v[92:95]
	v_mfma_f32_16x16x32_bf16 v[88:91], v[236:239], v[204:207], v[88:91]
	v_mfma_f32_16x16x32_bf16 v[76:79], v[228:231], v[212:215], v[76:79]
	v_mfma_f32_16x16x32_bf16 v[72:75], v[236:239], v[212:215], v[72:75]
	v_mfma_f32_16x16x32_bf16 v[68:71], v[228:231], v[220:223], v[68:71]
	v_mfma_f32_16x16x32_bf16 v[64:67], v[236:239], v[220:223], v[64:67]
	s_barrier
	s_mov_b32 m0, s35
	s_add_u32 s86, s24, 0x80
	s_addc_u32 s87, s25, 0
	ds_read_b128 v[164:167], v173 offset:16384
	ds_read_b128 v[174:177], v173 offset:17408
	ds_read_b128 v[200:203], v173 offset:18432
	ds_read_b128 v[204:207], v173 offset:19456
	ds_read_b128 v[208:211], v173 offset:20480
	ds_read_b128 v[212:215], v173 offset:21504
	ds_read_b128 v[216:219], v173 offset:22528
	ds_read_b128 v[220:223], v173 offset:23552
	global_load_lds_dwordx4 v148, s[24:25]
	s_mov_b32 m0, s36
	s_nop 0
	global_load_lds_dwordx4 v140, s[24:25]
	s_barrier
	s_waitcnt lgkmcnt(0)
	v_mfma_f32_16x16x32_bf16 v[60:63], v[128:131], v[164:167], v[60:63]
	v_mfma_f32_16x16x32_bf16 v[56:59], v[136:139], v[164:167], v[56:59]
	v_mfma_f32_16x16x32_bf16 v[52:55], v[128:131], v[200:203], v[52:55]
	v_mfma_f32_16x16x32_bf16 v[48:51], v[136:139], v[200:203], v[48:51]
	v_mfma_f32_16x16x32_bf16 v[36:39], v[128:131], v[208:211], v[36:39]
	v_mfma_f32_16x16x32_bf16 v[32:35], v[136:139], v[208:211], v[32:35]
	v_mfma_f32_16x16x32_bf16 v[20:23], v[128:131], v[216:219], v[20:23]
	v_mfma_f32_16x16x32_bf16 v[16:19], v[136:139], v[216:219], v[16:19]
	v_mfma_f32_16x16x32_bf16 v[60:63], v[132:135], v[174:177], v[60:63]
	v_mfma_f32_16x16x32_bf16 v[56:59], v[160:163], v[174:177], v[56:59]
	v_mfma_f32_16x16x32_bf16 v[52:55], v[132:135], v[204:207], v[52:55]
	v_mfma_f32_16x16x32_bf16 v[48:51], v[160:163], v[204:207], v[48:51]
	v_mfma_f32_16x16x32_bf16 v[36:39], v[132:135], v[212:215], v[36:39]
	v_mfma_f32_16x16x32_bf16 v[32:35], v[160:163], v[212:215], v[32:35]
	v_mfma_f32_16x16x32_bf16 v[20:23], v[132:135], v[220:223], v[20:23]
	v_mfma_f32_16x16x32_bf16 v[16:19], v[160:163], v[220:223], v[16:19]
	s_barrier
	s_add_u32 s16, s22, 0x160000
	s_addc_u32 s17, s23, 0
	s_add_i32 s54, s55, s29
	s_mov_b32 m0, s54
	s_nop 0
	global_load_lds_dwordx4 v148, s[16:17]
	s_add_i32 m0, s54, 0x2000
	s_nop 0
	global_load_lds_dwordx4 v140, s[16:17]
	s_waitcnt vmcnt(6)
	s_barrier
; #define PG8_STAGE(bufoff, gbase, voff) do { _Pragma("unroll") for (int _i = 0; _i < 2; ++_i) \
;         __builtin_amdgcn_global_load_lds((const unsigned*)((const char*)(gbase) + (voff)[_i]), (LAS unsigned*)(lds + (bufoff) + ldsw + _i * 8192), 16, 0, 0); } while (0)
; #define PG8_LDA(dst, b, h) do { _Pragma("unroll") for (int m = 0; m < 4; ++m) _Pragma("unroll") for (int k = 0; k < 2; ++k) dst[m][k] = *(const LAS bf16x8*)(lds + PG8_SA(b, h) + aoff + m * 2048 + k * 1024); } while (0)
; #define PG8_LDB(dst, b, h) do { _Pragma("unroll") for (int n = 0; n < 2; ++n) _Pragma("unroll") for (int k = 0; k < 2; ++k) dst[n][k] = *(const LAS bf16x8*)(lds + PG8_SB(b, h) + boff + n * 2048 + k * 1024); } while (0)
; #define PG8_MMA(ai, bj, At, Bt) do { __builtin_amdgcn_s_setprio(1); _Pragma("unroll") for (int m = 0; m < 4; ++m) _Pragma("unroll") for (int n = 0; n < 2; ++n) _Pragma("unroll") for (int k = 0; k < 2; ++k) \
;         acc[ai][bj][m][n] = __builtin_amdgcn_mfma_f32_16x16x32_bf16(Bt[n][k], At[m][k], acc[ai][bj][m][n], 0, 0, 0); __builtin_amdgcn_s_setprio(0); } while (0)
; #define PG8_WAIT_V(n) asm volatile("s_waitcnt vmcnt(" #n ")" ::: "memory")
; #define PG8_WAIT_L(n) asm volatile("s_waitcnt lgkmcnt(" #n ")" ::: "memory")
; #define PG8_BAR __builtin_amdgcn_s_barrier()
; #define PG8_SCHED __builtin_amdgcn_sched_barrier(0)
; template <class Epi, class Sched>
; __device__ __forceinline__ void gemm_phase(LAS unsigned char* lds, const Gemm g, const Sched& S, const Epi& E) {
;     ...
;             PG8_WAIT_V(6); PG8_BAR; PG8_MMA(1, 1, At, B1); PG8_BAR;
;             PG8_LDB(B0, 1, 0); PG8_SCHED; PG8_LDA(At, 1, 0); PG8_STAGE(PG8_SA(0, 1), a2 + hstep, voffA);
;             PG8_WAIT_L(8); PG8_BAR; PG8_WAIT_L(0); PG8_MMA(0, 0, At, B0); PG8_BAR; PG8_SCHED;
;             PG8_LDB(B1, 1, 1); PG8_STAGE(PG8_SB(1, 0), b3, voffB);
;             PG8_BAR; PG8_WAIT_L(0); PG8_MMA(0, 1, At, B1); PG8_BAR;
;             PG8_LDA(At, 1, 1); PG8_STAGE(PG8_SA(1, 0), a3, voffA);
;             PG8_BAR; PG8_WAIT_L(0); PG8_MMA(1, 0, At, B0); PG8_BAR; PG8_SCHED;
	v_mfma_f32_16x16x32_bf16 v[44:47], v[224:227], v[164:167], v[44:47]
	v_mfma_f32_16x16x32_bf16 v[40:43], v[232:235], v[164:167], v[40:43]
	v_mfma_f32_16x16x32_bf16 v[28:31], v[224:227], v[200:203], v[28:31]
	v_mfma_f32_16x16x32_bf16 v[24:27], v[232:235], v[200:203], v[24:27]
	v_mfma_f32_16x16x32_bf16 v[12:15], v[224:227], v[208:211], v[12:15]
	v_mfma_f32_16x16x32_bf16 v[8:11], v[232:235], v[208:211], v[8:11]
	v_mfma_f32_16x16x32_bf16 v[4:7], v[224:227], v[216:219], v[4:7]
	v_mfma_f32_16x16x32_bf16 v[0:3], v[232:235], v[216:219], v[0:3]
	v_mfma_f32_16x16x32_bf16 v[44:47], v[228:231], v[174:177], v[44:47]
	v_mfma_f32_16x16x32_bf16 v[40:43], v[236:239], v[174:177], v[40:43]
	v_mfma_f32_16x16x32_bf16 v[28:31], v[228:231], v[204:207], v[28:31]
	v_mfma_f32_16x16x32_bf16 v[24:27], v[236:239], v[204:207], v[24:27]
	v_mfma_f32_16x16x32_bf16 v[12:15], v[228:231], v[212:215], v[12:15]
	v_mfma_f32_16x16x32_bf16 v[8:11], v[236:239], v[212:215], v[8:11]
	v_mfma_f32_16x16x32_bf16 v[4:7], v[228:231], v[220:223], v[4:7]
	v_mfma_f32_16x16x32_bf16 v[0:3], v[236:239], v[220:223], v[0:3]
	s_barrier
	s_add_i32 s54, 0, 0x18000
	ds_read_b128 v[128:131], v141 offset:32768
	ds_read_b128 v[132:135], v141 offset:33792
	ds_read_b128 v[136:139], v141 offset:34816
	ds_read_b128 v[160:163], v141 offset:35840
	s_add_u32 s16, s24, 0x160000
	s_addc_u32 s17, s25, 0
	s_mov_b32 m0, s37
	ds_read_b128 v[164:167], v173 offset:32768
	ds_read_b128 v[174:177], v173 offset:33792
	ds_read_b128 v[200:203], v173 offset:34816
	ds_read_b128 v[204:207], v173 offset:35840
	ds_read_b128 v[208:211], v173 offset:36864
	ds_read_b128 v[212:215], v173 offset:37888
	ds_read_b128 v[216:219], v173 offset:38912
	ds_read_b128 v[220:223], v173 offset:39936
	global_load_lds_dwordx4 v148, s[16:17]
	s_mov_b32 m0, s38
	s_nop 0
	global_load_lds_dwordx4 v140, s[16:17]
	s_waitcnt lgkmcnt(8)
	s_barrier
	s_waitcnt lgkmcnt(7)
	v_mfma_f32_16x16x32_bf16 v[124:127], v[128:131], v[164:167], v[124:127]
	v_mfma_f32_16x16x32_bf16 v[120:123], v[136:139], v[164:167], v[120:123]
	s_waitcnt lgkmcnt(5)
	v_mfma_f32_16x16x32_bf16 v[116:119], v[128:131], v[200:203], v[116:119]
	v_mfma_f32_16x16x32_bf16 v[112:115], v[136:139], v[200:203], v[112:115]
	s_waitcnt lgkmcnt(3)
	v_mfma_f32_16x16x32_bf16 v[100:103], v[128:131], v[208:211], v[100:103]
	v_mfma_f32_16x16x32_bf16 v[96:99], v[136:139], v[208:211], v[96:99]
	s_waitcnt lgkmcnt(1)
	v_mfma_f32_16x16x32_bf16 v[84:87], v[128:131], v[216:219], v[84:87]
	v_mfma_f32_16x16x32_bf16 v[80:83], v[136:139], v[216:219], v[80:83]
	v_mfma_f32_16x16x32_bf16 v[124:127], v[132:135], v[174:177], v[124:127]
	v_mfma_f32_16x16x32_bf16 v[120:123], v[160:163], v[174:177], v[120:123]
	v_mfma_f32_16x16x32_bf16 v[116:119], v[132:135], v[204:207], v[116:119]
	v_mfma_f32_16x16x32_bf16 v[112:115], v[160:163], v[204:207], v[112:115]
	v_mfma_f32_16x16x32_bf16 v[100:103], v[132:135], v[212:215], v[100:103]
	v_mfma_f32_16x16x32_bf16 v[96:99], v[160:163], v[212:215], v[96:99]
	s_waitcnt lgkmcnt(0)
	v_mfma_f32_16x16x32_bf16 v[84:87], v[132:135], v[220:223], v[84:87]
	v_mfma_f32_16x16x32_bf16 v[80:83], v[160:163], v[220:223], v[80:83]
	s_barrier
	s_add_i32 s24, 0, 0x1c000
	s_add_i32 s16, s54, s29
	s_mov_b32 m0, s16
	ds_read_b128 v[224:227], v141 offset:49152
	ds_read_b128 v[228:231], v141 offset:50176
	ds_read_b128 v[232:235], v141 offset:51200
	ds_read_b128 v[236:239], v141 offset:52224
	global_load_lds_dwordx4 v148, s[84:85]
	s_add_i32 m0, s16, 0x2000
	s_nop 0
	global_load_lds_dwordx4 v140, s[84:85]
	s_barrier
	s_waitcnt lgkmcnt(0)
	v_mfma_f32_16x16x32_bf16 v[108:111], v[224:227], v[164:167], v[108:111]
	v_mfma_f32_16x16x32_bf16 v[104:107], v[232:235], v[164:167], v[104:107]
	v_mfma_f32_16x16x32_bf16 v[92:95], v[224:227], v[200:203], v[92:95]
	v_mfma_f32_16x16x32_bf16 v[88:91], v[232:235], v[200:203], v[88:91]
	v_mfma_f32_16x16x32_bf16 v[76:79], v[224:227], v[208:211], v[76:79]
	v_mfma_f32_16x16x32_bf16 v[72:75], v[232:235], v[208:211], v[72:75]
	v_mfma_f32_16x16x32_bf16 v[68:71], v[224:227], v[216:219], v[68:71]
	v_mfma_f32_16x16x32_bf16 v[64:67], v[232:235], v[216:219], v[64:67]
	v_mfma_f32_16x16x32_bf16 v[108:111], v[228:231], v[174:177], v[108:111]
	v_mfma_f32_16x16x32_bf16 v[104:107], v[236:239], v[174:177], v[104:107]
	v_mfma_f32_16x16x32_bf16 v[92:95], v[228:231], v[204:207], v[92:95]
	v_mfma_f32_16x16x32_bf16 v[88:91], v[236:239], v[204:207], v[88:91]
	v_mfma_f32_16x16x32_bf16 v[76:79], v[228:231], v[212:215], v[76:79]
	v_mfma_f32_16x16x32_bf16 v[72:75], v[236:239], v[212:215], v[72:75]
	v_mfma_f32_16x16x32_bf16 v[68:71], v[228:231], v[220:223], v[68:71]
	v_mfma_f32_16x16x32_bf16 v[64:67], v[236:239], v[220:223], v[64:67]
	s_barrier
	s_mov_b32 m0, s41
	ds_read_b128 v[164:167], v173 offset:49152
	ds_read_b128 v[174:177], v173 offset:50176
	ds_read_b128 v[200:203], v173 offset:51200
	ds_read_b128 v[204:207], v173 offset:52224
	ds_read_b128 v[208:211], v173 offset:53248
	ds_read_b128 v[212:215], v173 offset:54272
	ds_read_b128 v[216:219], v173 offset:55296
	ds_read_b128 v[220:223], v173 offset:56320
	global_load_lds_dwordx4 v148, s[86:87]
	s_mov_b32 m0, s42
	s_nop 0
	global_load_lds_dwordx4 v140, s[86:87]
	s_barrier
; #define PG8_STAGE(bufoff, gbase, voff) do { _Pragma("unroll") for (int _i = 0; _i < 2; ++_i) \
;         __builtin_amdgcn_global_load_lds((const unsigned*)((const char*)(gbase) + (voff)[_i]), (LAS unsigned*)(lds + (bufoff) + ldsw + _i * 8192), 16, 0, 0); } while (0)
; #define PG8_MMA(ai, bj, At, Bt) do { __builtin_amdgcn_s_setprio(1); _Pragma("unroll") for (int m = 0; m < 4; ++m) _Pragma("unroll") for (int n = 0; n < 2; ++n) _Pragma("unroll") for (int k = 0; k < 2; ++k) \
;         acc[ai][bj][m][n] = __builtin_amdgcn_mfma_f32_16x16x32_bf16(Bt[n][k], At[m][k], acc[ai][bj][m][n], 0, 0, 0); __builtin_amdgcn_s_setprio(0); } while (0)
; #define PG8_WAIT_V(n) asm volatile("s_waitcnt vmcnt(" #n ")" ::: "memory")
; #define PG8_WAIT_L(n) asm volatile("s_waitcnt lgkmcnt(" #n ")" ::: "memory")
; #define PG8_BAR __builtin_amdgcn_s_barrier()
; #define PG8_SCHED __builtin_amdgcn_sched_barrier(0)
;     __device__ __forceinline__ void operator()(const f32x4 (&acc)[2][2][4][2], const Unit& u, int wr, int wc, int fr, int fq) const {
;     ...
;         const float* base = (u.pm < 32) ? base_lo : base_hi;
; #pragma unroll
;         for (int ai = 0; ai < 2; ++ai) {
;             f32x4 bs[4][2][2];
; #pragma unroll
;             for (int m = 0; m < 4; ++m) { const size_t off = (size_t)(row0 + ai * HALF + m * 16) * DM + col0;
; #pragma unroll
;                 for (int bj = 0; bj < 2; ++bj)
; #pragma unroll
;                     for (int n = 0; n < 2; ++n) bs[m][bj][n] = *(const f32x4*)(base + off + bj * HALF + n * 16); }
; template <class Epi, class Sched>
; __device__ __forceinline__ void gemm_phase(LAS unsigned char* lds, const Gemm g, const Sched& S, const Epi& E) {
;     ...
;             PG8_BAR; PG8_WAIT_L(0); PG8_MMA(1, 0, At, B0); PG8_BAR; PG8_SCHED;
;             PG8_STAGE(PG8_SB(1, 1), b3 + hstep, voffB);
;             PG8_WAIT_V(6); PG8_BAR; PG8_MMA(1, 1, At, B1); PG8_BAR;
	s_waitcnt lgkmcnt(0)
	v_mfma_f32_16x16x32_bf16 v[60:63], v[128:131], v[164:167], v[60:63]
	v_mfma_f32_16x16x32_bf16 v[56:59], v[136:139], v[164:167], v[56:59]
	v_mfma_f32_16x16x32_bf16 v[52:55], v[128:131], v[200:203], v[52:55]
	v_mfma_f32_16x16x32_bf16 v[48:51], v[136:139], v[200:203], v[48:51]
	v_mfma_f32_16x16x32_bf16 v[36:39], v[128:131], v[208:211], v[36:39]
	v_mfma_f32_16x16x32_bf16 v[32:35], v[136:139], v[208:211], v[32:35]
	v_mfma_f32_16x16x32_bf16 v[20:23], v[128:131], v[216:219], v[20:23]
	v_mfma_f32_16x16x32_bf16 v[16:19], v[136:139], v[216:219], v[16:19]
	v_mfma_f32_16x16x32_bf16 v[60:63], v[132:135], v[174:177], v[60:63]
	v_mfma_f32_16x16x32_bf16 v[56:59], v[160:163], v[174:177], v[56:59]
	v_mfma_f32_16x16x32_bf16 v[52:55], v[132:135], v[204:207], v[52:55]
	v_mfma_f32_16x16x32_bf16 v[48:51], v[160:163], v[204:207], v[48:51]
	v_mfma_f32_16x16x32_bf16 v[36:39], v[132:135], v[212:215], v[36:39]
	v_mfma_f32_16x16x32_bf16 v[32:35], v[160:163], v[212:215], v[32:35]
	v_mfma_f32_16x16x32_bf16 v[20:23], v[132:135], v[220:223], v[20:23]
	v_mfma_f32_16x16x32_bf16 v[16:19], v[160:163], v[220:223], v[16:19]
	s_barrier
	s_add_u32 s16, s22, 0x160080
	s_addc_u32 s17, s23, 0
	s_add_i32 s22, s24, s29
	s_mov_b32 m0, s22
	s_nop 0
	global_load_lds_dwordx4 v148, s[16:17]
	s_add_i32 m0, s22, 0x2000
	s_nop 0
	global_load_lds_dwordx4 v140, s[16:17]
	s_add_u32 s51, s51, 0x100
	s_addc_u32 s52, s52, 0
	s_cmp_ge_i32 s53, s50
	s_mov_b64 s[16:17], s[20:21]
	s_mov_b32 s22, s53
	s_waitcnt vmcnt(6)
	s_barrier
	v_mfma_f32_16x16x32_bf16 v[44:47], v[224:227], v[164:167], v[44:47]
	v_mfma_f32_16x16x32_bf16 v[40:43], v[232:235], v[164:167], v[40:43]
	v_mfma_f32_16x16x32_bf16 v[28:31], v[224:227], v[200:203], v[28:31]
	v_mfma_f32_16x16x32_bf16 v[24:27], v[232:235], v[200:203], v[24:27]
	v_mfma_f32_16x16x32_bf16 v[12:15], v[224:227], v[208:211], v[12:15]
	v_mfma_f32_16x16x32_bf16 v[8:11], v[232:235], v[208:211], v[8:11]
	v_mfma_f32_16x16x32_bf16 v[4:7], v[224:227], v[216:219], v[4:7]
	v_mfma_f32_16x16x32_bf16 v[0:3], v[232:235], v[216:219], v[0:3]
	v_mfma_f32_16x16x32_bf16 v[44:47], v[228:231], v[174:177], v[44:47]
	v_mfma_f32_16x16x32_bf16 v[40:43], v[236:239], v[174:177], v[40:43]
	v_mfma_f32_16x16x32_bf16 v[28:31], v[228:231], v[204:207], v[28:31]
	v_mfma_f32_16x16x32_bf16 v[24:27], v[236:239], v[204:207], v[24:27]
	v_mfma_f32_16x16x32_bf16 v[12:15], v[228:231], v[212:215], v[12:15]
	v_mfma_f32_16x16x32_bf16 v[8:11], v[236:239], v[212:215], v[8:11]
	v_mfma_f32_16x16x32_bf16 v[4:7], v[228:231], v[220:223], v[4:7]
	v_mfma_f32_16x16x32_bf16 v[0:3], v[236:239], v[220:223], v[0:3]
	s_barrier
	s_cbranch_scc0 .LBB0_170
	v_lshl_add_u32 v146, s48, 8, v170
	v_lshl_or_b32 v160, s49, 8, v172
	s_mov_b64 s[16:17], -1
	s_cmp_lt_i32 s82, 0
	v_ashrrev_i32_e32 v161, 31, v160
	v_ashrrev_i32_e32 v147, 31, v146
	s_cbranch_scc0 .LBB0_173
	s_cmp_lt_i32 s48, 32
	s_cselect_b32 s17, s13, s61
	s_cselect_b32 s16, s12, s60
	v_lshlrev_b64 v[162:163], 2, v[160:161]
	v_lshl_add_u64 v[164:165], s[16:17], 0, v[162:163]
	v_lshlrev_b64 v[166:167], 13, v[146:147]
	v_lshl_add_u64 v[128:129], v[164:165], 0, v[166:167]
	global_load_dwordx4 v[174:177], v[128:129], off
	global_load_dwordx4 v[200:203], v[128:129], off offset:64
	global_load_dwordx4 v[204:207], v[128:129], off offset:512
	global_load_dwordx4 v[208:211], v[128:129], off offset:576
	v_or_b32_e32 v128, 16, v146
	v_ashrrev_i32_e32 v129, 31, v128
	v_lshlrev_b64 v[248:249], 13, v[128:129]
	v_lshl_add_u64 v[128:129], v[164:165], 0, v[248:249]
	global_load_dwordx4 v[212:215], v[128:129], off
	global_load_dwordx4 v[216:219], v[128:129], off offset:64
	global_load_dwordx4 v[220:223], v[128:129], off offset:512
	global_load_dwordx4 v[224:227], v[128:129], off offset:576
	v_or_b32_e32 v128, 32, v146
	v_ashrrev_i32_e32 v129, 31, v128
	v_lshlrev_b64 v[188:189], 13, v[128:129]
	v_lshl_add_u64 v[128:129], v[164:165], 0, v[188:189]
	global_load_dwordx4 v[228:231], v[128:129], off
	global_load_dwordx4 v[232:235], v[128:129], off offset:64
	global_load_dwordx4 v[236:239], v[128:129], off offset:512
	global_load_dwordx4 v[240:243], v[128:129], off offset:576
	v_or_b32_e32 v128, 48, v146
	v_ashrrev_i32_e32 v129, 31, v128
	v_lshlrev_b64 v[168:169], 13, v[128:129]
	v_lshl_add_u64 v[128:129], v[164:165], 0, v[168:169]
	global_load_dwordx4 v[244:247], v[128:129], off
	global_load_dwordx4 v[136:139], v[128:129], off offset:64
	global_load_dwordx4 v[132:135], v[128:129], off offset:512
	s_nop 0
	global_load_dwordx4 v[128:131], v[128:129], off offset:576
	v_lshl_add_u64 v[190:191], s[60:61], 0, v[166:167]
	v_lshl_add_u64 v[190:191], v[190:191], 0, v[162:163]
	v_lshl_add_u64 v[188:189], s[60:61], 0, v[188:189]
	v_lshl_add_u64 v[188:189], v[188:189], 0, v[162:163]
	v_lshl_add_u64 v[168:169], s[60:61], 0, v[168:169]
	v_lshl_add_u64 v[168:169], v[168:169], 0, v[162:163]
	s_mov_b64 s[16:17], 0x100000
	s_waitcnt vmcnt(0)
;     __device__ __forceinline__ void operator()(const f32x4 (&acc)[2][2][4][2], const Unit& u, int wr, int wc, int fr, int fq) const {
;     ...
;             for (int m = 0; m < 4; ++m) { const size_t off = (size_t)(row0 + ai * HALF + m * 16) * DM + col0;
; #pragma unroll
;                 for (int bj = 0; bj < 2; ++bj)
; #pragma unroll
;                     for (int n = 0; n < 2; ++n) bs[m][bj][n] = *(const f32x4*)(base + off + bj * HALF + n * 16); }
; #pragma unroll
;             for (int m = 0; m < 4; ++m) { const size_t off = (size_t)(row0 + ai * HALF + m * 16) * DM + col0;
; #pragma unroll
;                 for (int bj = 0; bj < 2; ++bj)
; #pragma unroll
;                     for (int n = 0; n < 2; ++n) *(f32x4*)(out + off + bj * HALF + n * 16) = bs[m][bj][n] + scale * acc[ai][bj][m][n]; }
	v_pk_fma_f32 v[176:177], v[126:127], 0.5, v[176:177] op_sel_hi:[1,0,1]
	v_pk_fma_f32 v[174:175], v[124:125], 0.5, v[174:175] op_sel_hi:[1,0,1]
	global_store_dwordx4 v[190:191], v[174:177], off
	v_pk_fma_f32 v[138:139], v[82:83], 0.5, v[138:139] op_sel_hi:[1,0,1]
	s_nop 0
	v_pk_fma_f32 v[176:177], v[122:123], 0.5, v[202:203] op_sel_hi:[1,0,1]
	v_pk_fma_f32 v[174:175], v[120:121], 0.5, v[200:201] op_sel_hi:[1,0,1]
	global_store_dwordx4 v[190:191], v[174:177], off offset:64
	v_pk_fma_f32 v[136:137], v[80:81], 0.5, v[136:137] op_sel_hi:[1,0,1]
	v_pk_fma_f32 v[134:135], v[70:71], 0.5, v[134:135] op_sel_hi:[1,0,1]
	v_pk_fma_f32 v[176:177], v[110:111], 0.5, v[206:207] op_sel_hi:[1,0,1]
	v_pk_fma_f32 v[174:175], v[108:109], 0.5, v[204:205] op_sel_hi:[1,0,1]
	global_store_dwordx4 v[190:191], v[174:177], off offset:512
	v_pk_fma_f32 v[132:133], v[68:69], 0.5, v[132:133] op_sel_hi:[1,0,1]
	v_pk_fma_f32 v[130:131], v[66:67], 0.5, v[130:131] op_sel_hi:[1,0,1]
	v_pk_fma_f32 v[176:177], v[106:107], 0.5, v[210:211] op_sel_hi:[1,0,1]
	v_pk_fma_f32 v[174:175], v[104:105], 0.5, v[208:209] op_sel_hi:[1,0,1]
	global_store_dwordx4 v[190:191], v[174:177], off offset:576
	v_lshl_add_u64 v[190:191], s[60:61], 0, v[248:249]
	v_lshl_add_u64 v[190:191], v[190:191], 0, v[162:163]
	v_pk_fma_f32 v[176:177], v[118:119], 0.5, v[214:215] op_sel_hi:[1,0,1]
	v_pk_fma_f32 v[174:175], v[116:117], 0.5, v[212:213] op_sel_hi:[1,0,1]
	global_store_dwordx4 v[190:191], v[174:177], off
	v_pk_fma_f32 v[128:129], v[64:65], 0.5, v[128:129] op_sel_hi:[1,0,1]
	global_store_dwordx4 v[168:169], v[136:139], off offset:64
	v_pk_fma_f32 v[176:177], v[114:115], 0.5, v[218:219] op_sel_hi:[1,0,1]
	v_pk_fma_f32 v[174:175], v[112:113], 0.5, v[216:217] op_sel_hi:[1,0,1]
	global_store_dwordx4 v[190:191], v[174:177], off offset:64
	global_store_dwordx4 v[168:169], v[132:135], off offset:512
	global_store_dwordx4 v[168:169], v[128:131], off offset:576
	v_pk_fma_f32 v[176:177], v[94:95], 0.5, v[222:223] op_sel_hi:[1,0,1]
	v_pk_fma_f32 v[174:175], v[92:93], 0.5, v[220:221] op_sel_hi:[1,0,1]
	global_store_dwordx4 v[190:191], v[174:177], off offset:512
	s_nop 1
	v_pk_fma_f32 v[176:177], v[90:91], 0.5, v[226:227] op_sel_hi:[1,0,1]
	v_pk_fma_f32 v[174:175], v[88:89], 0.5, v[224:225] op_sel_hi:[1,0,1]
	global_store_dwordx4 v[190:191], v[174:177], off offset:576
	s_nop 1
	v_pk_fma_f32 v[176:177], v[102:103], 0.5, v[230:231] op_sel_hi:[1,0,1]
	v_pk_fma_f32 v[174:175], v[100:101], 0.5, v[228:229] op_sel_hi:[1,0,1]
	global_store_dwordx4 v[188:189], v[174:177], off
	s_nop 1
	v_pk_fma_f32 v[176:177], v[98:99], 0.5, v[234:235] op_sel_hi:[1,0,1]
	v_pk_fma_f32 v[174:175], v[96:97], 0.5, v[232:233] op_sel_hi:[1,0,1]
	global_store_dwordx4 v[188:189], v[174:177], off offset:64
	s_nop 1
	v_pk_fma_f32 v[176:177], v[78:79], 0.5, v[238:239] op_sel_hi:[1,0,1]
	v_pk_fma_f32 v[174:175], v[76:77], 0.5, v[236:237] op_sel_hi:[1,0,1]
	global_store_dwordx4 v[188:189], v[174:177], off offset:512
	s_nop 1
	v_pk_fma_f32 v[176:177], v[74:75], 0.5, v[242:243] op_sel_hi:[1,0,1]
	v_pk_fma_f32 v[174:175], v[72:73], 0.5, v[240:241] op_sel_hi:[1,0,1]
	global_store_dwordx4 v[188:189], v[174:177], off offset:576
	s_nop 1
	v_pk_fma_f32 v[176:177], v[86:87], 0.5, v[246:247] op_sel_hi:[1,0,1]
	v_pk_fma_f32 v[174:175], v[84:85], 0.5, v[244:245] op_sel_hi:[1,0,1]
	global_store_dwordx4 v[168:169], v[174:177], off
	v_lshl_add_u64 v[168:169], v[166:167], 0, s[16:17]
	v_lshl_add_u64 v[128:129], v[164:165], 0, v[168:169]
	global_load_dwordx4 v[174:177], v[128:129], off
	global_load_dwordx4 v[200:203], v[128:129], off offset:64
	global_load_dwordx4 v[204:207], v[128:129], off offset:512
	global_load_dwordx4 v[208:211], v[128:129], off offset:576
	s_mov_b64 s[16:17], 0x120000
	v_lshl_add_u64 v[188:189], v[166:167], 0, s[16:17]
	v_lshl_add_u64 v[128:129], v[164:165], 0, v[188:189]
	global_load_dwordx4 v[212:215], v[128:129], off
	global_load_dwordx4 v[216:219], v[128:129], off offset:64
	global_load_dwordx4 v[220:223], v[128:129], off offset:512
	global_load_dwordx4 v[224:227], v[128:129], off offset:576
	s_mov_b64 s[16:17], 0x140000
	v_lshl_add_u64 v[190:191], v[166:167], 0, s[16:17]
	v_lshl_add_u64 v[128:129], v[164:165], 0, v[190:191]
	s_mov_b64 s[16:17], 0x160000
	global_load_dwordx4 v[228:231], v[128:129], off
	global_load_dwordx4 v[232:235], v[128:129], off offset:64
	global_load_dwordx4 v[236:239], v[128:129], off offset:512
	global_load_dwordx4 v[240:243], v[128:129], off offset:576
	v_lshl_add_u64 v[166:167], v[166:167], 0, s[16:17]
	v_lshl_add_u64 v[128:129], v[164:165], 0, v[166:167]
	global_load_dwordx4 v[244:247], v[128:129], off
	global_load_dwordx4 v[136:139], v[128:129], off offset:64
	global_load_dwordx4 v[132:135], v[128:129], off offset:512
	s_nop 0
	global_load_dwordx4 v[128:131], v[128:129], off offset:576
	v_lshl_add_u64 v[164:165], s[60:61], 0, v[168:169]
	v_lshl_add_u64 v[164:165], v[164:165], 0, v[162:163]
	s_mov_b64 s[16:17], 0
	s_waitcnt vmcnt(0)
;     __device__ __forceinline__ void operator()(const f32x4 (&acc)[2][2][4][2], const Unit& u, int wr, int wc, int fr, int fq) const {
;     ...
;             for (int m = 0; m < 4; ++m) { const size_t off = (size_t)(row0 + ai * HALF + m * 16) * DM + col0;
; #pragma unroll
;                 for (int bj = 0; bj < 2; ++bj)
; #pragma unroll
;                     for (int n = 0; n < 2; ++n) *(f32x4*)(out + off + bj * HALF + n * 16) = bs[m][bj][n] + scale * acc[ai][bj][m][n]; }
	v_pk_fma_f32 v[176:177], v[62:63], 0.5, v[176:177] op_sel_hi:[1,0,1]
	v_pk_fma_f32 v[174:175], v[60:61], 0.5, v[174:175] op_sel_hi:[1,0,1]
	global_store_dwordx4 v[164:165], v[174:177], off
	v_pk_fma_f32 v[138:139], v[18:19], 0.5, v[138:139] op_sel_hi:[1,0,1]
	s_nop 0
	v_pk_fma_f32 v[176:177], v[58:59], 0.5, v[202:203] op_sel_hi:[1,0,1]
	v_pk_fma_f32 v[174:175], v[56:57], 0.5, v[200:201] op_sel_hi:[1,0,1]
	global_store_dwordx4 v[164:165], v[174:177], off offset:64
	v_pk_fma_f32 v[136:137], v[16:17], 0.5, v[136:137] op_sel_hi:[1,0,1]
	v_pk_fma_f32 v[134:135], v[6:7], 0.5, v[134:135] op_sel_hi:[1,0,1]
	v_pk_fma_f32 v[176:177], v[46:47], 0.5, v[206:207] op_sel_hi:[1,0,1]
	v_pk_fma_f32 v[174:175], v[44:45], 0.5, v[204:205] op_sel_hi:[1,0,1]
	global_store_dwordx4 v[164:165], v[174:177], off offset:512
	v_pk_fma_f32 v[132:133], v[4:5], 0.5, v[132:133] op_sel_hi:[1,0,1]
	v_pk_fma_f32 v[130:131], v[2:3], 0.5, v[130:131] op_sel_hi:[1,0,1]
	v_pk_fma_f32 v[176:177], v[42:43], 0.5, v[210:211] op_sel_hi:[1,0,1]
	v_pk_fma_f32 v[174:175], v[40:41], 0.5, v[208:209] op_sel_hi:[1,0,1]
	global_store_dwordx4 v[164:165], v[174:177], off offset:576
	v_lshl_add_u64 v[164:165], s[60:61], 0, v[188:189]
	v_lshl_add_u64 v[164:165], v[164:165], 0, v[162:163]
	v_pk_fma_f32 v[176:177], v[54:55], 0.5, v[214:215] op_sel_hi:[1,0,1]
	v_pk_fma_f32 v[174:175], v[52:53], 0.5, v[212:213] op_sel_hi:[1,0,1]
	global_store_dwordx4 v[164:165], v[174:177], off
	v_pk_fma_f32 v[128:129], v[0:1], 0.5, v[128:129] op_sel_hi:[1,0,1]
	s_nop 0
	v_pk_fma_f32 v[176:177], v[50:51], 0.5, v[218:219] op_sel_hi:[1,0,1]
	v_pk_fma_f32 v[174:175], v[48:49], 0.5, v[216:217] op_sel_hi:[1,0,1]
	global_store_dwordx4 v[164:165], v[174:177], off offset:64
	s_nop 1
	v_pk_fma_f32 v[176:177], v[30:31], 0.5, v[222:223] op_sel_hi:[1,0,1]
	v_pk_fma_f32 v[174:175], v[28:29], 0.5, v[220:221] op_sel_hi:[1,0,1]
	global_store_dwordx4 v[164:165], v[174:177], off offset:512
	s_nop 1
	v_pk_fma_f32 v[176:177], v[26:27], 0.5, v[226:227] op_sel_hi:[1,0,1]
	v_pk_fma_f32 v[174:175], v[24:25], 0.5, v[224:225] op_sel_hi:[1,0,1]
	global_store_dwordx4 v[164:165], v[174:177], off offset:576
	v_lshl_add_u64 v[164:165], s[60:61], 0, v[190:191]
	v_lshl_add_u64 v[164:165], v[164:165], 0, v[162:163]
	v_pk_fma_f32 v[176:177], v[38:39], 0.5, v[230:231] op_sel_hi:[1,0,1]
	v_pk_fma_f32 v[174:175], v[36:37], 0.5, v[228:229] op_sel_hi:[1,0,1]
	global_store_dwordx4 v[164:165], v[174:177], off
	s_nop 1
	v_pk_fma_f32 v[176:177], v[34:35], 0.5, v[234:235] op_sel_hi:[1,0,1]
	v_pk_fma_f32 v[174:175], v[32:33], 0.5, v[232:233] op_sel_hi:[1,0,1]
	global_store_dwordx4 v[164:165], v[174:177], off offset:64
	s_nop 1
	v_pk_fma_f32 v[176:177], v[14:15], 0.5, v[238:239] op_sel_hi:[1,0,1]
	v_pk_fma_f32 v[174:175], v[12:13], 0.5, v[236:237] op_sel_hi:[1,0,1]
	global_store_dwordx4 v[164:165], v[174:177], off offset:512
	s_nop 1
	v_pk_fma_f32 v[176:177], v[10:11], 0.5, v[242:243] op_sel_hi:[1,0,1]
	v_pk_fma_f32 v[174:175], v[8:9], 0.5, v[240:241] op_sel_hi:[1,0,1]
	global_store_dwordx4 v[164:165], v[174:177], off offset:576
	v_lshl_add_u64 v[164:165], s[60:61], 0, v[166:167]
	v_lshl_add_u64 v[162:163], v[164:165], 0, v[162:163]
	v_pk_fma_f32 v[176:177], v[22:23], 0.5, v[246:247] op_sel_hi:[1,0,1]
	v_pk_fma_f32 v[174:175], v[20:21], 0.5, v[244:245] op_sel_hi:[1,0,1]
	global_store_dwordx4 v[162:163], v[174:177], off
	global_store_dwordx4 v[162:163], v[136:139], off offset:64
	global_store_dwordx4 v[162:163], v[132:135], off offset:512
	global_store_dwordx4 v[162:163], v[128:131], off offset:576

; #define PG8_STAGE(bufoff, gbase, voff) do { _Pragma("unroll") for (int _i = 0; _i < 2; ++_i) \
;         __builtin_amdgcn_global_load_lds((const unsigned*)((const char*)(gbase) + (voff)[_i]), (LAS unsigned*)(lds + (bufoff) + ldsw + _i * 8192), 16, 0, 0); } while (0)
; #define PG8_LDA(dst, b, h) do { _Pragma("unroll") for (int m = 0; m < 4; ++m) _Pragma("unroll") for (int k = 0; k < 2; ++k) dst[m][k] = *(const LAS bf16x8*)(lds + PG8_SA(b, h) + aoff + m * 2048 + k * 1024); } while (0)
; #define PG8_LDB(dst, b, h) do { _Pragma("unroll") for (int n = 0; n < 2; ++n) _Pragma("unroll") for (int k = 0; k < 2; ++k) dst[n][k] = *(const LAS bf16x8*)(lds + PG8_SB(b, h) + boff + n * 2048 + k * 1024); } while (0)
; #define PG8_MMA(ai, bj, At, Bt) do { __builtin_amdgcn_s_setprio(1); _Pragma("unroll") for (int m = 0; m < 4; ++m) _Pragma("unroll") for (int n = 0; n < 2; ++n) _Pragma("unroll") for (int k = 0; k < 2; ++k) \
;         acc[ai][bj][m][n] = __builtin_amdgcn_mfma_f32_16x16x32_bf16(Bt[n][k], At[m][k], acc[ai][bj][m][n], 0, 0, 0); __builtin_amdgcn_s_setprio(0); } while (0)
; #define PG8_WAIT_V(n) asm volatile("s_waitcnt vmcnt(" #n ")" ::: "memory")
; #define PG8_WAIT_L(n) asm volatile("s_waitcnt lgkmcnt(" #n ")" ::: "memory")
; #define PG8_BAR __builtin_amdgcn_s_barrier()
; template <class Epi, class Sched>
; __device__ __forceinline__ void gemm_phase(LAS unsigned char* lds, const Gemm g, const Sched& S, const Epi& E) {
;     ...
;             const bool last = (t == nt - 2);
;             const char* a1 = cA + (size_t)(t + 1) * kstep;
;             const char* a2 = last ? nA : cA + (size_t)(t + 2) * kstep; const char* b2 = last ? nB : cB + (size_t)(t + 2) * kstep;
;             const char* a3 = a2 + kstep; const char* b3 = b2 + kstep;
;             PG8_LDB(B0, 0, 0); PG8_SCHED; PG8_LDA(At, 0, 0); PG8_STAGE(PG8_SA(1, 1), a1 + hstep, voffA);
;             PG8_WAIT_L(8); PG8_BAR; PG8_WAIT_L(0); PG8_MMA(0, 0, At, B0); PG8_BAR; PG8_SCHED;
;             PG8_LDB(B1, 0, 1); PG8_STAGE(PG8_SB(0, 0), b2, voffB);
;             PG8_BAR; PG8_WAIT_L(0); PG8_MMA(0, 1, At, B1); PG8_BAR;
;             PG8_LDA(At, 0, 1); PG8_STAGE(PG8_SA(0, 0), a2, voffA);
;             PG8_BAR; PG8_WAIT_L(0); PG8_MMA(1, 0, At, B0); PG8_BAR; PG8_SCHED;
;             PG8_STAGE(PG8_SB(0, 1), b2 + hstep, voffB);
;             PG8_WAIT_V(6); PG8_BAR; PG8_MMA(1, 1, At, B1); PG8_BAR;
.LBB0_213:
	s_add_u32 s20, s16, 0xfff80080
	s_addc_u32 s21, s17, -1
	s_add_i32 s45, 0, 0x10000
	ds_read_b128 v[144:147], v129
	ds_read_b128 v[160:163], v129 offset:1024
	ds_read_b128 v[164:167], v129 offset:2048
	ds_read_b128 v[168:171], v129 offset:3072
	s_cmp_eq_u32 s44, 28
	s_cselect_b32 s23, s11, s21
	s_cselect_b32 s22, s40, s20
	s_cselect_b32 s21, s7, s43
	s_cselect_b32 s20, s41, s42
	s_add_i32 m0, s30, 0xc000
	ds_read_b128 v[172:175], v143
	ds_read_b128 v[200:203], v143 offset:1024
	ds_read_b128 v[204:207], v143 offset:2048
	ds_read_b128 v[208:211], v143 offset:3072
	ds_read_b128 v[212:215], v143 offset:4096
	ds_read_b128 v[216:219], v143 offset:5120
	ds_read_b128 v[220:223], v143 offset:6144
	ds_read_b128 v[224:227], v143 offset:7168
	global_load_lds_dwordx4 v134, s[16:17]
	s_add_i32 m0, s30, 0xe000
	s_nop 0
	global_load_lds_dwordx4 v136, s[16:17]
	s_waitcnt lgkmcnt(8)
	s_barrier
	s_waitcnt lgkmcnt(7)
	v_mfma_f32_16x16x32_bf16 v[124:127], v[144:147], v[172:175], v[124:127]
	v_mfma_f32_16x16x32_bf16 v[116:119], v[164:167], v[172:175], v[116:119]
	s_waitcnt lgkmcnt(5)
	v_mfma_f32_16x16x32_bf16 v[108:111], v[144:147], v[204:207], v[108:111]
	v_mfma_f32_16x16x32_bf16 v[100:103], v[164:167], v[204:207], v[100:103]
	s_waitcnt lgkmcnt(3)
	v_mfma_f32_16x16x32_bf16 v[92:95], v[144:147], v[212:215], v[92:95]
	v_mfma_f32_16x16x32_bf16 v[84:87], v[164:167], v[212:215], v[84:87]
	s_waitcnt lgkmcnt(1)
	v_mfma_f32_16x16x32_bf16 v[76:79], v[144:147], v[220:223], v[76:79]
	v_mfma_f32_16x16x32_bf16 v[68:71], v[164:167], v[220:223], v[68:71]
	v_mfma_f32_16x16x32_bf16 v[124:127], v[160:163], v[200:203], v[124:127]
	v_mfma_f32_16x16x32_bf16 v[116:119], v[168:171], v[200:203], v[116:119]
	v_mfma_f32_16x16x32_bf16 v[108:111], v[160:163], v[208:211], v[108:111]
	v_mfma_f32_16x16x32_bf16 v[100:103], v[168:171], v[208:211], v[100:103]
	v_mfma_f32_16x16x32_bf16 v[92:95], v[160:163], v[216:219], v[92:95]
	v_mfma_f32_16x16x32_bf16 v[84:87], v[168:171], v[216:219], v[84:87]
	s_waitcnt lgkmcnt(0)
	v_mfma_f32_16x16x32_bf16 v[76:79], v[160:163], v[224:227], v[76:79]
	v_mfma_f32_16x16x32_bf16 v[68:71], v[168:171], v[224:227], v[68:71]
	s_barrier
	s_add_i32 s48, 0, 0x14000
	s_add_i32 s45, s45, s29
	ds_read_b128 v[228:231], v129 offset:16384
	ds_read_b128 v[232:235], v129 offset:17408
	ds_read_b128 v[236:239], v129 offset:18432
	ds_read_b128 v[240:243], v129 offset:19456
	s_add_u32 s84, s20, 0x80
	s_addc_u32 s85, s21, 0
	s_mov_b32 m0, s45
	s_nop 0
	global_load_lds_dwordx4 v148, s[20:21]
	s_add_i32 m0, s45, 0x2000
	s_nop 0
	global_load_lds_dwordx4 v128, s[20:21]
	s_barrier
	s_waitcnt lgkmcnt(0)
	v_mfma_f32_16x16x32_bf16 v[120:123], v[228:231], v[172:175], v[120:123]
	v_mfma_f32_16x16x32_bf16 v[112:115], v[236:239], v[172:175], v[112:115]
	v_mfma_f32_16x16x32_bf16 v[104:107], v[228:231], v[204:207], v[104:107]
	v_mfma_f32_16x16x32_bf16 v[96:99], v[236:239], v[204:207], v[96:99]
	v_mfma_f32_16x16x32_bf16 v[88:91], v[228:231], v[212:215], v[88:91]
	v_mfma_f32_16x16x32_bf16 v[80:83], v[236:239], v[212:215], v[80:83]
	v_mfma_f32_16x16x32_bf16 v[72:75], v[228:231], v[220:223], v[72:75]
	v_mfma_f32_16x16x32_bf16 v[64:67], v[236:239], v[220:223], v[64:67]
	v_mfma_f32_16x16x32_bf16 v[120:123], v[232:235], v[200:203], v[120:123]
	v_mfma_f32_16x16x32_bf16 v[112:115], v[240:243], v[200:203], v[112:115]
	v_mfma_f32_16x16x32_bf16 v[104:107], v[232:235], v[208:211], v[104:107]
	v_mfma_f32_16x16x32_bf16 v[96:99], v[240:243], v[208:211], v[96:99]
	v_mfma_f32_16x16x32_bf16 v[88:91], v[232:235], v[216:219], v[88:91]
	v_mfma_f32_16x16x32_bf16 v[80:83], v[240:243], v[216:219], v[80:83]
	v_mfma_f32_16x16x32_bf16 v[72:75], v[232:235], v[224:227], v[72:75]
	v_mfma_f32_16x16x32_bf16 v[64:67], v[240:243], v[224:227], v[64:67]
	s_barrier
	s_mov_b32 m0, s30
	s_add_u32 s86, s22, 0x80
	s_addc_u32 s87, s23, 0
	ds_read_b128 v[172:175], v143 offset:16384
	ds_read_b128 v[200:203], v143 offset:17408
	ds_read_b128 v[204:207], v143 offset:18432
	ds_read_b128 v[208:211], v143 offset:19456
	ds_read_b128 v[212:215], v143 offset:20480
	ds_read_b128 v[216:219], v143 offset:21504
	ds_read_b128 v[220:223], v143 offset:22528
	ds_read_b128 v[224:227], v143 offset:23552
	global_load_lds_dwordx4 v132, s[22:23]
	s_mov_b32 m0, s31
	s_nop 0
	global_load_lds_dwordx4 v130, s[22:23]
	s_barrier
	s_waitcnt lgkmcnt(0)
	v_mfma_f32_16x16x32_bf16 v[60:63], v[144:147], v[172:175], v[60:63]
	v_mfma_f32_16x16x32_bf16 v[52:55], v[164:167], v[172:175], v[52:55]
	v_mfma_f32_16x16x32_bf16 v[44:47], v[144:147], v[204:207], v[44:47]
	v_mfma_f32_16x16x32_bf16 v[36:39], v[164:167], v[204:207], v[36:39]
	v_mfma_f32_16x16x32_bf16 v[28:31], v[144:147], v[212:215], v[28:31]
	v_mfma_f32_16x16x32_bf16 v[20:23], v[164:167], v[212:215], v[20:23]
	v_mfma_f32_16x16x32_bf16 v[12:15], v[144:147], v[220:223], v[12:15]
	v_mfma_f32_16x16x32_bf16 v[4:7], v[164:167], v[220:223], v[4:7]
	v_mfma_f32_16x16x32_bf16 v[60:63], v[160:163], v[200:203], v[60:63]
	v_mfma_f32_16x16x32_bf16 v[52:55], v[168:171], v[200:203], v[52:55]
	v_mfma_f32_16x16x32_bf16 v[44:47], v[160:163], v[208:211], v[44:47]
	v_mfma_f32_16x16x32_bf16 v[36:39], v[168:171], v[208:211], v[36:39]
	v_mfma_f32_16x16x32_bf16 v[28:31], v[160:163], v[216:219], v[28:31]
	v_mfma_f32_16x16x32_bf16 v[20:23], v[168:171], v[216:219], v[20:23]
	v_mfma_f32_16x16x32_bf16 v[12:15], v[160:163], v[224:227], v[12:15]
	v_mfma_f32_16x16x32_bf16 v[4:7], v[168:171], v[224:227], v[4:7]
	s_barrier
	s_add_u32 s46, s20, 0x80000
	s_addc_u32 s47, s21, 0
	s_add_i32 s45, s48, s29
	s_mov_b32 m0, s45
	s_nop 0
	global_load_lds_dwordx4 v148, s[46:47]
	s_add_i32 m0, s45, 0x2000
	s_nop 0
	global_load_lds_dwordx4 v128, s[46:47]
	s_waitcnt vmcnt(6)
	s_barrier
; #define PG8_STAGE(bufoff, gbase, voff) do { _Pragma("unroll") for (int _i = 0; _i < 2; ++_i) \
;         __builtin_amdgcn_global_load_lds((const unsigned*)((const char*)(gbase) + (voff)[_i]), (LAS unsigned*)(lds + (bufoff) + ldsw + _i * 8192), 16, 0, 0); } while (0)
; #define PG8_LDA(dst, b, h) do { _Pragma("unroll") for (int m = 0; m < 4; ++m) _Pragma("unroll") for (int k = 0; k < 2; ++k) dst[m][k] = *(const LAS bf16x8*)(lds + PG8_SA(b, h) + aoff + m * 2048 + k * 1024); } while (0)
; #define PG8_LDB(dst, b, h) do { _Pragma("unroll") for (int n = 0; n < 2; ++n) _Pragma("unroll") for (int k = 0; k < 2; ++k) dst[n][k] = *(const LAS bf16x8*)(lds + PG8_SB(b, h) + boff + n * 2048 + k * 1024); } while (0)
; #define PG8_MMA(ai, bj, At, Bt) do { __builtin_amdgcn_s_setprio(1); _Pragma("unroll") for (int m = 0; m < 4; ++m) _Pragma("unroll") for (int n = 0; n < 2; ++n) _Pragma("unroll") for (int k = 0; k < 2; ++k) \
;         acc[ai][bj][m][n] = __builtin_amdgcn_mfma_f32_16x16x32_bf16(Bt[n][k], At[m][k], acc[ai][bj][m][n], 0, 0, 0); __builtin_amdgcn_s_setprio(0); } while (0)
; #define PG8_WAIT_V(n) asm volatile("s_waitcnt vmcnt(" #n ")" ::: "memory")
; #define PG8_WAIT_L(n) asm volatile("s_waitcnt lgkmcnt(" #n ")" ::: "memory")
; #define PG8_BAR __builtin_amdgcn_s_barrier()
; #define PG8_SCHED __builtin_amdgcn_sched_barrier(0)
; template <class Epi, class Sched>
; __device__ __forceinline__ void gemm_phase(LAS unsigned char* lds, const Gemm g, const Sched& S, const Epi& E) {
;     ...
;             PG8_WAIT_V(6); PG8_BAR; PG8_MMA(1, 1, At, B1); PG8_BAR;
;             PG8_LDB(B0, 1, 0); PG8_SCHED; PG8_LDA(At, 1, 0); PG8_STAGE(PG8_SA(0, 1), a2 + hstep, voffA);
;             PG8_WAIT_L(8); PG8_BAR; PG8_WAIT_L(0); PG8_MMA(0, 0, At, B0); PG8_BAR; PG8_SCHED;
;             PG8_LDB(B1, 1, 1); PG8_STAGE(PG8_SB(1, 0), b3, voffB);
;             PG8_BAR; PG8_WAIT_L(0); PG8_MMA(0, 1, At, B1); PG8_BAR;
;             PG8_LDA(At, 1, 1); PG8_STAGE(PG8_SA(1, 0), a3, voffA);
;             PG8_BAR; PG8_WAIT_L(0); PG8_MMA(1, 0, At, B0); PG8_BAR; PG8_SCHED;
	v_mfma_f32_16x16x32_bf16 v[56:59], v[228:231], v[172:175], v[56:59]
	v_mfma_f32_16x16x32_bf16 v[48:51], v[236:239], v[172:175], v[48:51]
	v_mfma_f32_16x16x32_bf16 v[40:43], v[228:231], v[204:207], v[40:43]
	v_mfma_f32_16x16x32_bf16 v[32:35], v[236:239], v[204:207], v[32:35]
	v_mfma_f32_16x16x32_bf16 v[24:27], v[228:231], v[212:215], v[24:27]
	v_mfma_f32_16x16x32_bf16 v[16:19], v[236:239], v[212:215], v[16:19]
	v_mfma_f32_16x16x32_bf16 v[8:11], v[228:231], v[220:223], v[8:11]
	v_mfma_f32_16x16x32_bf16 v[0:3], v[236:239], v[220:223], v[0:3]
	v_mfma_f32_16x16x32_bf16 v[56:59], v[232:235], v[200:203], v[56:59]
	v_mfma_f32_16x16x32_bf16 v[48:51], v[240:243], v[200:203], v[48:51]
	v_mfma_f32_16x16x32_bf16 v[40:43], v[232:235], v[208:211], v[40:43]
	v_mfma_f32_16x16x32_bf16 v[32:35], v[240:243], v[208:211], v[32:35]
	v_mfma_f32_16x16x32_bf16 v[24:27], v[232:235], v[216:219], v[24:27]
	v_mfma_f32_16x16x32_bf16 v[16:19], v[240:243], v[216:219], v[16:19]
	v_mfma_f32_16x16x32_bf16 v[8:11], v[232:235], v[224:227], v[8:11]
	v_mfma_f32_16x16x32_bf16 v[0:3], v[240:243], v[224:227], v[0:3]
	s_barrier
	s_add_i32 s45, 0, 0x18000
	ds_read_b128 v[144:147], v129 offset:32768
	ds_read_b128 v[160:163], v129 offset:33792
	ds_read_b128 v[164:167], v129 offset:34816
	ds_read_b128 v[168:171], v129 offset:35840
	s_add_u32 s22, s22, 0x80000
	s_addc_u32 s23, s23, 0
	s_mov_b32 m0, s33
	ds_read_b128 v[172:175], v143 offset:32768
	ds_read_b128 v[200:203], v143 offset:33792
	ds_read_b128 v[204:207], v143 offset:34816
	ds_read_b128 v[208:211], v143 offset:35840
	ds_read_b128 v[212:215], v143 offset:36864
	ds_read_b128 v[216:219], v143 offset:37888
	ds_read_b128 v[220:223], v143 offset:38912
	ds_read_b128 v[224:227], v143 offset:39936
	global_load_lds_dwordx4 v132, s[22:23]
	s_mov_b32 m0, s34
	s_nop 0
	global_load_lds_dwordx4 v130, s[22:23]
	s_waitcnt lgkmcnt(8)
	s_barrier
	s_waitcnt lgkmcnt(7)
	v_mfma_f32_16x16x32_bf16 v[124:127], v[144:147], v[172:175], v[124:127]
	v_mfma_f32_16x16x32_bf16 v[116:119], v[164:167], v[172:175], v[116:119]
	s_waitcnt lgkmcnt(5)
	v_mfma_f32_16x16x32_bf16 v[108:111], v[144:147], v[204:207], v[108:111]
	v_mfma_f32_16x16x32_bf16 v[100:103], v[164:167], v[204:207], v[100:103]
	s_waitcnt lgkmcnt(3)
	v_mfma_f32_16x16x32_bf16 v[92:95], v[144:147], v[212:215], v[92:95]
	v_mfma_f32_16x16x32_bf16 v[84:87], v[164:167], v[212:215], v[84:87]
	s_waitcnt lgkmcnt(1)
	v_mfma_f32_16x16x32_bf16 v[76:79], v[144:147], v[220:223], v[76:79]
	v_mfma_f32_16x16x32_bf16 v[68:71], v[164:167], v[220:223], v[68:71]
	v_mfma_f32_16x16x32_bf16 v[124:127], v[160:163], v[200:203], v[124:127]
	v_mfma_f32_16x16x32_bf16 v[116:119], v[168:171], v[200:203], v[116:119]
	v_mfma_f32_16x16x32_bf16 v[108:111], v[160:163], v[208:211], v[108:111]
	v_mfma_f32_16x16x32_bf16 v[100:103], v[168:171], v[208:211], v[100:103]
	v_mfma_f32_16x16x32_bf16 v[92:95], v[160:163], v[216:219], v[92:95]
	v_mfma_f32_16x16x32_bf16 v[84:87], v[168:171], v[216:219], v[84:87]
	s_waitcnt lgkmcnt(0)
	v_mfma_f32_16x16x32_bf16 v[76:79], v[160:163], v[224:227], v[76:79]
	v_mfma_f32_16x16x32_bf16 v[68:71], v[168:171], v[224:227], v[68:71]
	s_barrier
	s_add_i32 s22, 0, 0x1c000
	s_add_i32 s23, s45, s29
	s_mov_b32 m0, s23
	ds_read_b128 v[228:231], v129 offset:49152
	ds_read_b128 v[232:235], v129 offset:50176
	ds_read_b128 v[236:239], v129 offset:51200
	ds_read_b128 v[240:243], v129 offset:52224
	global_load_lds_dwordx4 v148, s[84:85]
	s_add_i32 m0, s23, 0x2000
	s_nop 0
	global_load_lds_dwordx4 v128, s[84:85]
	s_barrier
	s_waitcnt lgkmcnt(0)
	v_mfma_f32_16x16x32_bf16 v[120:123], v[228:231], v[172:175], v[120:123]
	v_mfma_f32_16x16x32_bf16 v[112:115], v[236:239], v[172:175], v[112:115]
	v_mfma_f32_16x16x32_bf16 v[104:107], v[228:231], v[204:207], v[104:107]
	v_mfma_f32_16x16x32_bf16 v[96:99], v[236:239], v[204:207], v[96:99]
	v_mfma_f32_16x16x32_bf16 v[88:91], v[228:231], v[212:215], v[88:91]
	v_mfma_f32_16x16x32_bf16 v[80:83], v[236:239], v[212:215], v[80:83]
	v_mfma_f32_16x16x32_bf16 v[72:75], v[228:231], v[220:223], v[72:75]
	v_mfma_f32_16x16x32_bf16 v[64:67], v[236:239], v[220:223], v[64:67]
	v_mfma_f32_16x16x32_bf16 v[120:123], v[232:235], v[200:203], v[120:123]
	v_mfma_f32_16x16x32_bf16 v[112:115], v[240:243], v[200:203], v[112:115]
	v_mfma_f32_16x16x32_bf16 v[104:107], v[232:235], v[208:211], v[104:107]
	v_mfma_f32_16x16x32_bf16 v[96:99], v[240:243], v[208:211], v[96:99]
	v_mfma_f32_16x16x32_bf16 v[88:91], v[232:235], v[216:219], v[88:91]
	v_mfma_f32_16x16x32_bf16 v[80:83], v[240:243], v[216:219], v[80:83]
	v_mfma_f32_16x16x32_bf16 v[72:75], v[232:235], v[224:227], v[72:75]
	v_mfma_f32_16x16x32_bf16 v[64:67], v[240:243], v[224:227], v[64:67]
	s_barrier
	s_mov_b32 m0, s35
	ds_read_b128 v[172:175], v143 offset:49152
	ds_read_b128 v[200:203], v143 offset:50176
	ds_read_b128 v[204:207], v143 offset:51200
	ds_read_b128 v[208:211], v143 offset:52224
	ds_read_b128 v[212:215], v143 offset:53248
	ds_read_b128 v[216:219], v143 offset:54272
	ds_read_b128 v[220:223], v143 offset:55296
	ds_read_b128 v[224:227], v143 offset:56320
	global_load_lds_dwordx4 v132, s[86:87]
	s_mov_b32 m0, s36
	s_nop 0
	global_load_lds_dwordx4 v130, s[86:87]
	s_barrier
; __device__ __forceinline__ unsigned cvt_pk_bf16(float lo, float hi) { unsigned r; asm("v_cvt_pk_bf16_f32 %0, %1, %2" : "=v"(r) : "v"(lo), "v"(hi)); return r; }
; #define PG8_STAGE(bufoff, gbase, voff) do { _Pragma("unroll") for (int _i = 0; _i < 2; ++_i) \
;         __builtin_amdgcn_global_load_lds((const unsigned*)((const char*)(gbase) + (voff)[_i]), (LAS unsigned*)(lds + (bufoff) + ldsw + _i * 8192), 16, 0, 0); } while (0)
; #define PG8_MMA(ai, bj, At, Bt) do { __builtin_amdgcn_s_setprio(1); _Pragma("unroll") for (int m = 0; m < 4; ++m) _Pragma("unroll") for (int n = 0; n < 2; ++n) _Pragma("unroll") for (int k = 0; k < 2; ++k) \
;         acc[ai][bj][m][n] = __builtin_amdgcn_mfma_f32_16x16x32_bf16(Bt[n][k], At[m][k], acc[ai][bj][m][n], 0, 0, 0); __builtin_amdgcn_s_setprio(0); } while (0)
; #define PG8_WAIT_V(n) asm volatile("s_waitcnt vmcnt(" #n ")" ::: "memory")
; #define PG8_WAIT_L(n) asm volatile("s_waitcnt lgkmcnt(" #n ")" ::: "memory")
; #define PG8_BAR __builtin_amdgcn_s_barrier()
;     __device__ __forceinline__ void operator()(const f32x4 (&acc)[2][2][4][2], const Unit& u, int wr, int wc, int fr, int fq) const {
;         const int row0 = u.pm * BM + wr * 64 + fr, col0 = u.pn * HALF + wc * 32 + 8 * fq;
; #pragma unroll
;         for (int ai = 0; ai < 2; ++ai)
; #pragma unroll
;             for (int m = 0; m < 4; ++m) { bf16_t* rowp = O + (size_t)(row0 + ai * HALF + m * 16) * ldc + col0;
;                 float h[8];
; #pragma unroll
;                 for (int n = 0; n < 2; ++n)
; #pragma unroll
;                     for (int j = 0; j < 4; ++j) { const float g = acc[ai][0][m][n][j], up = acc[ai][1][m][n][j];
;                         const float e = __builtin_amdgcn_exp2f(-1.4426950408889634f * g);
;                         h[n * 4 + j] = g * __builtin_amdgcn_rcpf(1.0f + e) * up; }
;                 u32x4 w; w.x = cvt_pk_bf16(h[0], h[1]); w.y = cvt_pk_bf16(h[2], h[3]); w.z = cvt_pk_bf16(h[4], h[5]); w.w = cvt_pk_bf16(h[6], h[7]);
;                 *(u32x4*)rowp = w; }
; template <class Epi, class Sched>
; __device__ __forceinline__ void gemm_phase(LAS unsigned char* lds, const Gemm g, const Sched& S, const Epi& E) {
;     ...
;             PG8_BAR; PG8_WAIT_L(0); PG8_MMA(1, 0, At, B0); PG8_BAR; PG8_SCHED;
;             PG8_STAGE(PG8_SB(1, 1), b3 + hstep, voffB);
;             PG8_WAIT_V(6); PG8_BAR; PG8_MMA(1, 1, At, B1); PG8_BAR;
	s_waitcnt lgkmcnt(0)
	v_mfma_f32_16x16x32_bf16 v[60:63], v[144:147], v[172:175], v[60:63]
	v_mfma_f32_16x16x32_bf16 v[52:55], v[164:167], v[172:175], v[52:55]
	v_mfma_f32_16x16x32_bf16 v[44:47], v[144:147], v[204:207], v[44:47]
	v_mfma_f32_16x16x32_bf16 v[36:39], v[164:167], v[204:207], v[36:39]
	v_mfma_f32_16x16x32_bf16 v[28:31], v[144:147], v[212:215], v[28:31]
	v_mfma_f32_16x16x32_bf16 v[20:23], v[164:167], v[212:215], v[20:23]
	v_mfma_f32_16x16x32_bf16 v[12:15], v[144:147], v[220:223], v[12:15]
	v_mfma_f32_16x16x32_bf16 v[4:7], v[164:167], v[220:223], v[4:7]
	v_mfma_f32_16x16x32_bf16 v[60:63], v[160:163], v[200:203], v[60:63]
	v_mfma_f32_16x16x32_bf16 v[52:55], v[168:171], v[200:203], v[52:55]
	v_mfma_f32_16x16x32_bf16 v[44:47], v[160:163], v[208:211], v[44:47]
	v_mfma_f32_16x16x32_bf16 v[36:39], v[168:171], v[208:211], v[36:39]
	v_mfma_f32_16x16x32_bf16 v[28:31], v[160:163], v[216:219], v[28:31]
	v_mfma_f32_16x16x32_bf16 v[20:23], v[168:171], v[216:219], v[20:23]
	v_mfma_f32_16x16x32_bf16 v[12:15], v[160:163], v[224:227], v[12:15]
	v_mfma_f32_16x16x32_bf16 v[4:7], v[168:171], v[224:227], v[4:7]
	s_barrier
	s_add_u32 s20, s20, 0x80080
	s_addc_u32 s21, s21, 0
	s_add_i32 s22, s22, s29
	s_mov_b32 m0, s22
	s_nop 0
	global_load_lds_dwordx4 v148, s[20:21]
	s_add_i32 m0, s22, 0x2000
	s_nop 0
	global_load_lds_dwordx4 v128, s[20:21]
	s_add_i32 s44, s44, 2
	s_add_u32 s16, s16, 0x100
	s_addc_u32 s17, s17, 0
	s_add_u32 s42, s42, 0x100
	s_addc_u32 s43, s43, 0
	s_cmp_gt_u32 s44, 29
	s_waitcnt vmcnt(6)
	s_barrier
	v_mfma_f32_16x16x32_bf16 v[56:59], v[228:231], v[172:175], v[56:59]
	v_mfma_f32_16x16x32_bf16 v[48:51], v[236:239], v[172:175], v[48:51]
	v_mfma_f32_16x16x32_bf16 v[40:43], v[228:231], v[204:207], v[40:43]
	v_mfma_f32_16x16x32_bf16 v[32:35], v[236:239], v[204:207], v[32:35]
	v_mfma_f32_16x16x32_bf16 v[24:27], v[228:231], v[212:215], v[24:27]
	v_mfma_f32_16x16x32_bf16 v[16:19], v[236:239], v[212:215], v[16:19]
	v_mfma_f32_16x16x32_bf16 v[8:11], v[228:231], v[220:223], v[8:11]
	v_mfma_f32_16x16x32_bf16 v[0:3], v[236:239], v[220:223], v[0:3]
	v_mfma_f32_16x16x32_bf16 v[56:59], v[232:235], v[200:203], v[56:59]
	v_mfma_f32_16x16x32_bf16 v[48:51], v[240:243], v[200:203], v[48:51]
	v_mfma_f32_16x16x32_bf16 v[40:43], v[232:235], v[208:211], v[40:43]
	v_mfma_f32_16x16x32_bf16 v[32:35], v[240:243], v[208:211], v[32:35]
	v_mfma_f32_16x16x32_bf16 v[24:27], v[232:235], v[216:219], v[24:27]
	v_mfma_f32_16x16x32_bf16 v[16:19], v[240:243], v[216:219], v[16:19]
	v_mfma_f32_16x16x32_bf16 v[8:11], v[232:235], v[224:227], v[8:11]
	v_mfma_f32_16x16x32_bf16 v[0:3], v[240:243], v[224:227], v[0:3]
	s_barrier
	s_cbranch_scc0 .LBB0_213
	v_mul_f32_e32 v145, 0xbfb8aa3b, v124
	v_exp_f32_e32 v145, v145
	v_lshl_or_b32 v146, s38, 7, v142
	v_lshl_add_u32 v144, s39, 8, v140
	v_ashrrev_i32_e32 v147, 31, v146
	v_add_f32_e32 v145, 1.0, v145
	v_rcp_f32_e32 v145, v145
	v_mov_b64_e32 v[138:139], s[4:5]
	s_movk_i32 s7, 0x2c00
	v_mad_i64_i32 v[160:161], s[16:17], v144, s7, v[138:139]
	v_mul_f32_e32 v124, v124, v145
	v_mul_f32_e32 v120, v120, v124
	v_mul_f32_e32 v124, 0xbfb8aa3b, v125
	v_exp_f32_e32 v124, v124
	s_and_b64 vcc, exec, s[0:1]
	s_mov_b32 s38, s6
	s_mov_b32 s39, s10
	v_add_f32_e32 v124, 1.0, v124
	v_rcp_f32_e32 v124, v124
	s_mov_b64 s[20:21], s[14:15]
	v_mul_f32_e32 v124, v125, v124
	v_mul_f32_e32 v121, v121, v124
	v_mul_f32_e32 v124, 0xbfb8aa3b, v126
	v_exp_f32_e32 v124, v124
	s_nop 0
	v_add_f32_e32 v124, 1.0, v124
	v_rcp_f32_e32 v124, v124
	s_nop 0
	v_mul_f32_e32 v124, v126, v124
	v_mul_f32_e32 v122, v122, v124
	v_mul_f32_e32 v124, 0xbfb8aa3b, v127
	v_exp_f32_e32 v124, v124
	s_nop 0
	v_add_f32_e32 v124, 1.0, v124
	v_rcp_f32_e32 v124, v124
	s_nop 0
	v_mul_f32_e32 v124, v127, v124
	v_mul_f32_e32 v123, v123, v124
	v_mul_f32_e32 v124, 0xbfb8aa3b, v116
	v_exp_f32_e32 v124, v124
	s_nop 0
	v_add_f32_e32 v124, 1.0, v124
	v_rcp_f32_e32 v124, v124
	s_nop 0
	v_mul_f32_e32 v116, v116, v124
	v_mul_f32_e32 v116, v112, v116
	v_mul_f32_e32 v112, 0xbfb8aa3b, v117
	v_exp_f32_e32 v112, v112
	s_nop 0
	v_add_f32_e32 v112, 1.0, v112
	v_rcp_f32_e32 v112, v112
	s_nop 0
	v_mul_f32_e32 v112, v117, v112
	v_mul_f32_e32 v117, v113, v112
	v_mul_f32_e32 v112, 0xbfb8aa3b, v118
	v_exp_f32_e32 v112, v112
	v_cvt_pk_bf16_f32 v116, v116, v117
	s_nop 0
	v_add_f32_e32 v112, 1.0, v112
	v_rcp_f32_e32 v112, v112
	s_nop 0
	v_mul_f32_e32 v112, v118, v112
	v_mul_f32_e32 v124, v114, v112
	v_mul_f32_e32 v112, 0xbfb8aa3b, v119
	v_exp_f32_e32 v112, v112
	v_cvt_pk_bf16_f32 v114, v120, v121
	s_nop 0
	v_add_f32_e32 v112, 1.0, v112
	v_rcp_f32_e32 v112, v112
	s_nop 0
	v_mul_f32_e32 v112, v119, v112
	v_mul_f32_e32 v125, v115, v112
	v_lshlrev_b64 v[112:113], 1, v[146:147]
	v_lshl_add_u64 v[118:119], v[160:161], 0, v[112:113]
	v_cvt_pk_bf16_f32 v115, v122, v123
	v_cvt_pk_bf16_f32 v117, v124, v125
	global_store_dwordx4 v[118:119], v[114:117], off
	s_nop 1
	v_mul_f32_e32 v116, 0xbfb8aa3b, v108
	v_exp_f32_e32 v116, v116
	v_or_b32_e32 v114, 16, v144
	v_mad_i64_i32 v[114:115], s[16:17], v114, s7, v[138:139]
	v_add_f32_e32 v116, 1.0, v116
	v_rcp_f32_e32 v116, v116
	s_nop 0
	v_mul_f32_e32 v108, v108, v116
	v_mul_f32_e32 v104, v104, v108
	v_mul_f32_e32 v108, 0xbfb8aa3b, v109
	v_exp_f32_e32 v108, v108
	s_nop 0
	v_add_f32_e32 v108, 1.0, v108
	v_rcp_f32_e32 v108, v108
	s_nop 0
	v_mul_f32_e32 v108, v109, v108
	v_mul_f32_e32 v105, v105, v108
	v_mul_f32_e32 v108, 0xbfb8aa3b, v110
	v_exp_f32_e32 v108, v108
	s_nop 0
	v_add_f32_e32 v108, 1.0, v108
	v_rcp_f32_e32 v108, v108
	s_nop 0
	v_mul_f32_e32 v108, v110, v108
	v_mul_f32_e32 v106, v106, v108
	v_mul_f32_e32 v108, 0xbfb8aa3b, v111
	v_exp_f32_e32 v108, v108
	s_nop 0
	v_add_f32_e32 v108, 1.0, v108
; __device__ __forceinline__ unsigned cvt_pk_bf16(float lo, float hi) { unsigned r; asm("v_cvt_pk_bf16_f32 %0, %1, %2" : "=v"(r) : "v"(lo), "v"(hi)); return r; }
;     __device__ __forceinline__ void operator()(const f32x4 (&acc)[2][2][4][2], const Unit& u, int wr, int wc, int fr, int fq) const {
;         const int row0 = u.pm * BM + wr * 64 + fr, col0 = u.pn * HALF + wc * 32 + 8 * fq;
; #pragma unroll
;         for (int ai = 0; ai < 2; ++ai)
; #pragma unroll
;             for (int m = 0; m < 4; ++m) { bf16_t* rowp = O + (size_t)(row0 + ai * HALF + m * 16) * ldc + col0;
;                 float h[8];
; #pragma unroll
;                 for (int n = 0; n < 2; ++n)
; #pragma unroll
;                     for (int j = 0; j < 4; ++j) { const float g = acc[ai][0][m][n][j], up = acc[ai][1][m][n][j];
;                         const float e = __builtin_amdgcn_exp2f(-1.4426950408889634f * g);
;                         h[n * 4 + j] = g * __builtin_amdgcn_rcpf(1.0f + e) * up; }
;                 u32x4 w; w.x = cvt_pk_bf16(h[0], h[1]); w.y = cvt_pk_bf16(h[2], h[3]); w.z = cvt_pk_bf16(h[4], h[5]); w.w = cvt_pk_bf16(h[6], h[7]);
;                 *(u32x4*)rowp = w; }
	v_rcp_f32_e32 v108, v108
	s_nop 0
	v_mul_f32_e32 v108, v111, v108
	v_mul_f32_e32 v107, v107, v108
	v_mul_f32_e32 v108, 0xbfb8aa3b, v100
	v_exp_f32_e32 v108, v108
	s_nop 0
	v_add_f32_e32 v108, 1.0, v108
	v_rcp_f32_e32 v108, v108
	s_nop 0
	v_mul_f32_e32 v100, v100, v108
	v_mul_f32_e32 v108, v96, v100
	v_mul_f32_e32 v96, 0xbfb8aa3b, v101
	v_exp_f32_e32 v96, v96
	s_nop 0
	v_add_f32_e32 v96, 1.0, v96
	v_rcp_f32_e32 v96, v96
	s_nop 0
	v_mul_f32_e32 v96, v101, v96
	v_mul_f32_e32 v109, v97, v96
	v_mul_f32_e32 v96, 0xbfb8aa3b, v102
	v_exp_f32_e32 v96, v96
	v_lshl_add_u64 v[100:101], v[114:115], 0, v[112:113]
	v_cvt_pk_bf16_f32 v97, v106, v107
	v_add_f32_e32 v96, 1.0, v96
	v_rcp_f32_e32 v96, v96
	s_nop 0
	v_mul_f32_e32 v96, v102, v96
	v_mul_f32_e32 v102, v98, v96
	v_mul_f32_e32 v96, 0xbfb8aa3b, v103
	v_exp_f32_e32 v96, v96
	v_cvt_pk_bf16_f32 v98, v108, v109
	s_nop 0
	v_add_f32_e32 v96, 1.0, v96
	v_rcp_f32_e32 v96, v96
	s_nop 0
	v_mul_f32_e32 v96, v103, v96
	v_mul_f32_e32 v99, v99, v96
	v_cvt_pk_bf16_f32 v96, v104, v105
	v_cvt_pk_bf16_f32 v99, v102, v99
	global_store_dwordx4 v[100:101], v[96:99], off
	s_nop 1
	v_mul_f32_e32 v98, 0xbfb8aa3b, v92
	v_exp_f32_e32 v98, v98
	v_or_b32_e32 v96, 32, v144
	v_mad_i64_i32 v[96:97], s[16:17], v96, s7, v[138:139]
	v_add_f32_e32 v98, 1.0, v98
	v_rcp_f32_e32 v98, v98
	s_nop 0
	v_mul_f32_e32 v92, v92, v98
	v_mul_f32_e32 v88, v88, v92
	v_mul_f32_e32 v92, 0xbfb8aa3b, v93
	v_exp_f32_e32 v92, v92
	s_nop 0
	v_add_f32_e32 v92, 1.0, v92
	v_rcp_f32_e32 v92, v92
	s_nop 0
	v_mul_f32_e32 v92, v93, v92
	v_mul_f32_e32 v89, v89, v92
	v_mul_f32_e32 v92, 0xbfb8aa3b, v94
	v_exp_f32_e32 v92, v92
	s_nop 0
	v_add_f32_e32 v92, 1.0, v92
	v_rcp_f32_e32 v92, v92
	s_nop 0
	v_mul_f32_e32 v92, v94, v92
	v_mul_f32_e32 v90, v90, v92
	v_mul_f32_e32 v92, 0xbfb8aa3b, v95
	v_exp_f32_e32 v92, v92
	s_nop 0
	v_add_f32_e32 v92, 1.0, v92
	v_rcp_f32_e32 v92, v92
	s_nop 0
	v_mul_f32_e32 v92, v95, v92
	v_mul_f32_e32 v91, v91, v92
	v_mul_f32_e32 v92, 0xbfb8aa3b, v84
	v_exp_f32_e32 v92, v92
	s_nop 0
	v_add_f32_e32 v92, 1.0, v92
	v_rcp_f32_e32 v92, v92
	s_nop 0
	v_mul_f32_e32 v84, v84, v92
	v_mul_f32_e32 v92, v80, v84
	v_mul_f32_e32 v80, 0xbfb8aa3b, v85
	v_exp_f32_e32 v80, v80
	s_nop 0
	v_add_f32_e32 v80, 1.0, v80
	v_rcp_f32_e32 v80, v80
	s_nop 0
	v_mul_f32_e32 v80, v85, v80
	v_mul_f32_e32 v93, v81, v80
	v_mul_f32_e32 v80, 0xbfb8aa3b, v86
	v_exp_f32_e32 v80, v80
	v_lshl_add_u64 v[84:85], v[96:97], 0, v[112:113]
	v_cvt_pk_bf16_f32 v81, v90, v91
	v_add_f32_e32 v80, 1.0, v80
	v_rcp_f32_e32 v80, v80
	s_nop 0
	v_mul_f32_e32 v80, v86, v80
	v_mul_f32_e32 v86, v82, v80
	v_mul_f32_e32 v80, 0xbfb8aa3b, v87
	v_exp_f32_e32 v80, v80
	v_cvt_pk_bf16_f32 v82, v92, v93
	s_nop 0
	v_add_f32_e32 v80, 1.0, v80
	v_rcp_f32_e32 v80, v80
	s_nop 0
	v_mul_f32_e32 v80, v87, v80
	v_mul_f32_e32 v83, v83, v80
	v_cvt_pk_bf16_f32 v80, v88, v89
	v_cvt_pk_bf16_f32 v83, v86, v83
	global_store_dwordx4 v[84:85], v[80:83], off
	s_nop 1
	v_mul_f32_e32 v82, 0xbfb8aa3b, v76
	v_exp_f32_e32 v82, v82
	v_or_b32_e32 v80, 48, v144
	v_mad_i64_i32 v[80:81], s[16:17], v80, s7, v[138:139]
	v_add_f32_e32 v82, 1.0, v82
	v_rcp_f32_e32 v82, v82
	s_nop 0
	v_mul_f32_e32 v76, v76, v82
	v_mul_f32_e32 v72, v72, v76
	v_mul_f32_e32 v76, 0xbfb8aa3b, v77
	v_exp_f32_e32 v76, v76
	s_nop 0
	v_add_f32_e32 v76, 1.0, v76
	v_rcp_f32_e32 v76, v76
	s_nop 0
	v_mul_f32_e32 v76, v77, v76
	v_mul_f32_e32 v73, v73, v76
	v_mul_f32_e32 v76, 0xbfb8aa3b, v78
	v_exp_f32_e32 v76, v76
	s_nop 0
	v_add_f32_e32 v76, 1.0, v76
	v_rcp_f32_e32 v76, v76
	s_nop 0
	v_mul_f32_e32 v76, v78, v76
	v_mul_f32_e32 v74, v74, v76
	v_mul_f32_e32 v76, 0xbfb8aa3b, v79
	v_exp_f32_e32 v76, v76
	s_nop 0
	v_add_f32_e32 v76, 1.0, v76
	v_rcp_f32_e32 v76, v76
	s_nop 0
	v_mul_f32_e32 v76, v79, v76
	v_mul_f32_e32 v75, v75, v76
	v_mul_f32_e32 v76, 0xbfb8aa3b, v68
	v_exp_f32_e32 v76, v76
	s_nop 0
	v_add_f32_e32 v76, 1.0, v76
	v_rcp_f32_e32 v76, v76
	s_nop 0
	v_mul_f32_e32 v68, v68, v76
	v_mul_f32_e32 v76, v64, v68
	v_mul_f32_e32 v64, 0xbfb8aa3b, v69
	v_exp_f32_e32 v64, v64
	s_nop 0
	v_add_f32_e32 v64, 1.0, v64
	v_rcp_f32_e32 v64, v64
	s_nop 0
	v_mul_f32_e32 v64, v69, v64
	v_mul_f32_e32 v77, v65, v64
	v_mul_f32_e32 v64, 0xbfb8aa3b, v70
	v_exp_f32_e32 v64, v64
	v_lshl_add_u64 v[68:69], v[80:81], 0, v[112:113]
	v_cvt_pk_bf16_f32 v65, v74, v75
	v_add_f32_e32 v64, 1.0, v64
	v_rcp_f32_e32 v64, v64
	s_nop 0
	v_mul_f32_e32 v64, v70, v64
	v_mul_f32_e32 v70, v66, v64
	v_mul_f32_e32 v64, 0xbfb8aa3b, v71
	v_exp_f32_e32 v64, v64
	v_cvt_pk_bf16_f32 v66, v76, v77
	s_nop 0
	v_add_f32_e32 v64, 1.0, v64
	v_rcp_f32_e32 v64, v64
	s_nop 0
	v_mul_f32_e32 v64, v71, v64
	v_mul_f32_e32 v67, v67, v64
	v_cvt_pk_bf16_f32 v64, v72, v73
	v_cvt_pk_bf16_f32 v67, v70, v67
	global_store_dwordx4 v[68:69], v[64:67], off
	s_nop 1
	v_mul_f32_e32 v66, 0xbfb8aa3b, v60
	v_exp_f32_e32 v66, v66
	v_add_u32_e32 v64, 0x80, v144
	v_mad_i64_i32 v[64:65], s[16:17], v64, s7, v[138:139]
	v_add_f32_e32 v66, 1.0, v66
	v_rcp_f32_e32 v66, v66
	s_nop 0
	v_mul_f32_e32 v60, v60, v66
	v_mul_f32_e32 v56, v56, v60
	v_mul_f32_e32 v60, 0xbfb8aa3b, v61
	v_exp_f32_e32 v60, v60
	s_nop 0
	v_add_f32_e32 v60, 1.0, v60
	v_rcp_f32_e32 v60, v60
	s_nop 0
	v_mul_f32_e32 v60, v61, v60
	v_mul_f32_e32 v57, v57, v60
	v_mul_f32_e32 v60, 0xbfb8aa3b, v62
	v_exp_f32_e32 v60, v60
	s_nop 0
	v_add_f32_e32 v60, 1.0, v60
	v_rcp_f32_e32 v60, v60
	s_nop 0
	v_mul_f32_e32 v60, v62, v60
	v_mul_f32_e32 v58, v58, v60
	v_mul_f32_e32 v60, 0xbfb8aa3b, v63
	v_exp_f32_e32 v60, v60
	s_nop 0
	v_add_f32_e32 v60, 1.0, v60
	v_rcp_f32_e32 v60, v60
	s_nop 0
	v_mul_f32_e32 v60, v63, v60
	v_mul_f32_e32 v59, v59, v60
	v_mul_f32_e32 v60, 0xbfb8aa3b, v52
	v_exp_f32_e32 v60, v60
; __device__ __forceinline__ unsigned cvt_pk_bf16(float lo, float hi) { unsigned r; asm("v_cvt_pk_bf16_f32 %0, %1, %2" : "=v"(r) : "v"(lo), "v"(hi)); return r; }
;     __device__ __forceinline__ void operator()(const f32x4 (&acc)[2][2][4][2], const Unit& u, int wr, int wc, int fr, int fq) const {
;         const int row0 = u.pm * BM + wr * 64 + fr, col0 = u.pn * HALF + wc * 32 + 8 * fq;
; #pragma unroll
;         for (int ai = 0; ai < 2; ++ai)
; #pragma unroll
;             for (int m = 0; m < 4; ++m) { bf16_t* rowp = O + (size_t)(row0 + ai * HALF + m * 16) * ldc + col0;
;                 float h[8];
; #pragma unroll
;                 for (int n = 0; n < 2; ++n)
; #pragma unroll
;                     for (int j = 0; j < 4; ++j) { const float g = acc[ai][0][m][n][j], up = acc[ai][1][m][n][j];
;                         const float e = __builtin_amdgcn_exp2f(-1.4426950408889634f * g);
;                         h[n * 4 + j] = g * __builtin_amdgcn_rcpf(1.0f + e) * up; }
;                 u32x4 w; w.x = cvt_pk_bf16(h[0], h[1]); w.y = cvt_pk_bf16(h[2], h[3]); w.z = cvt_pk_bf16(h[4], h[5]); w.w = cvt_pk_bf16(h[6], h[7]);
;                 *(u32x4*)rowp = w; }
	s_nop 0
	v_add_f32_e32 v60, 1.0, v60
	v_rcp_f32_e32 v60, v60
	s_nop 0
	v_mul_f32_e32 v52, v52, v60
	v_mul_f32_e32 v60, v48, v52
	v_mul_f32_e32 v48, 0xbfb8aa3b, v53
	v_exp_f32_e32 v48, v48
	s_nop 0
	v_add_f32_e32 v48, 1.0, v48
	v_rcp_f32_e32 v48, v48
	s_nop 0
	v_mul_f32_e32 v48, v53, v48
	v_mul_f32_e32 v61, v49, v48
	v_mul_f32_e32 v48, 0xbfb8aa3b, v54
	v_exp_f32_e32 v48, v48
	v_lshl_add_u64 v[52:53], v[64:65], 0, v[112:113]
	v_cvt_pk_bf16_f32 v49, v58, v59
	v_add_f32_e32 v48, 1.0, v48
	v_rcp_f32_e32 v48, v48
	s_nop 0
	v_mul_f32_e32 v48, v54, v48
	v_mul_f32_e32 v54, v50, v48
	v_mul_f32_e32 v48, 0xbfb8aa3b, v55
	v_exp_f32_e32 v48, v48
	v_cvt_pk_bf16_f32 v50, v60, v61
	s_nop 0
	v_add_f32_e32 v48, 1.0, v48
	v_rcp_f32_e32 v48, v48
	s_nop 0
	v_mul_f32_e32 v48, v55, v48
	v_mul_f32_e32 v51, v51, v48
	v_cvt_pk_bf16_f32 v48, v56, v57
	v_cvt_pk_bf16_f32 v51, v54, v51
	global_store_dwordx4 v[52:53], v[48:51], off
	s_nop 1
	v_mul_f32_e32 v50, 0xbfb8aa3b, v44
	v_exp_f32_e32 v50, v50
	v_add_u32_e32 v48, 0x90, v144
	v_mad_i64_i32 v[48:49], s[16:17], v48, s7, v[138:139]
	v_add_f32_e32 v50, 1.0, v50
	v_rcp_f32_e32 v50, v50
	s_nop 0
	v_mul_f32_e32 v44, v44, v50
	v_mul_f32_e32 v40, v40, v44
	v_mul_f32_e32 v44, 0xbfb8aa3b, v45
	v_exp_f32_e32 v44, v44
	s_nop 0
	v_add_f32_e32 v44, 1.0, v44
	v_rcp_f32_e32 v44, v44
	s_nop 0
	v_mul_f32_e32 v44, v45, v44
	v_mul_f32_e32 v41, v41, v44
	v_mul_f32_e32 v44, 0xbfb8aa3b, v46
	v_exp_f32_e32 v44, v44
	s_nop 0
	v_add_f32_e32 v44, 1.0, v44
	v_rcp_f32_e32 v44, v44
	s_nop 0
	v_mul_f32_e32 v44, v46, v44
	v_mul_f32_e32 v42, v42, v44
	v_mul_f32_e32 v44, 0xbfb8aa3b, v47
	v_exp_f32_e32 v44, v44
	s_nop 0
	v_add_f32_e32 v44, 1.0, v44
	v_rcp_f32_e32 v44, v44
	s_nop 0
	v_mul_f32_e32 v44, v47, v44
	v_mul_f32_e32 v43, v43, v44
	v_mul_f32_e32 v44, 0xbfb8aa3b, v36
	v_exp_f32_e32 v44, v44
	s_nop 0
	v_add_f32_e32 v44, 1.0, v44
	v_rcp_f32_e32 v44, v44
	s_nop 0
	v_mul_f32_e32 v36, v36, v44
	v_mul_f32_e32 v44, v32, v36
	v_mul_f32_e32 v32, 0xbfb8aa3b, v37
	v_exp_f32_e32 v32, v32
	s_nop 0
	v_add_f32_e32 v32, 1.0, v32
	v_rcp_f32_e32 v32, v32
	s_nop 0
	v_mul_f32_e32 v32, v37, v32
	v_mul_f32_e32 v45, v33, v32
	v_mul_f32_e32 v32, 0xbfb8aa3b, v38
	v_exp_f32_e32 v32, v32
	v_lshl_add_u64 v[36:37], v[48:49], 0, v[112:113]
	v_cvt_pk_bf16_f32 v33, v42, v43
	v_add_f32_e32 v32, 1.0, v32
	v_rcp_f32_e32 v32, v32
	s_nop 0
	v_mul_f32_e32 v32, v38, v32
	v_mul_f32_e32 v38, v34, v32
	v_mul_f32_e32 v32, 0xbfb8aa3b, v39
	v_exp_f32_e32 v32, v32
	v_cvt_pk_bf16_f32 v34, v44, v45
	s_nop 0
	v_add_f32_e32 v32, 1.0, v32
	v_rcp_f32_e32 v32, v32
	s_nop 0
	v_mul_f32_e32 v32, v39, v32
	v_mul_f32_e32 v35, v35, v32
	v_cvt_pk_bf16_f32 v32, v40, v41
	v_cvt_pk_bf16_f32 v35, v38, v35
	global_store_dwordx4 v[36:37], v[32:35], off
	s_nop 1
	v_mul_f32_e32 v34, 0xbfb8aa3b, v28
	v_exp_f32_e32 v34, v34
	v_add_u32_e32 v32, 0xa0, v144
	v_mad_i64_i32 v[32:33], s[16:17], v32, s7, v[138:139]
	v_add_f32_e32 v34, 1.0, v34
	v_rcp_f32_e32 v34, v34
	s_nop 0
	v_mul_f32_e32 v28, v28, v34
	v_mul_f32_e32 v24, v24, v28
	v_mul_f32_e32 v28, 0xbfb8aa3b, v29
	v_exp_f32_e32 v28, v28
	s_nop 0
	v_add_f32_e32 v28, 1.0, v28
	v_rcp_f32_e32 v28, v28
	s_nop 0
	v_mul_f32_e32 v28, v29, v28
	v_mul_f32_e32 v25, v25, v28
	v_mul_f32_e32 v28, 0xbfb8aa3b, v30
	v_exp_f32_e32 v28, v28
	s_nop 0
	v_add_f32_e32 v28, 1.0, v28
	v_rcp_f32_e32 v28, v28
	s_nop 0
	v_mul_f32_e32 v28, v30, v28
	v_mul_f32_e32 v26, v26, v28
	v_mul_f32_e32 v28, 0xbfb8aa3b, v31
	v_exp_f32_e32 v28, v28
	s_nop 0
	v_add_f32_e32 v28, 1.0, v28
	v_rcp_f32_e32 v28, v28
	s_nop 0
	v_mul_f32_e32 v28, v31, v28
	v_mul_f32_e32 v27, v27, v28
	v_mul_f32_e32 v28, 0xbfb8aa3b, v20
	v_exp_f32_e32 v28, v28
	s_nop 0
	v_add_f32_e32 v28, 1.0, v28
	v_rcp_f32_e32 v28, v28
	s_nop 0
	v_mul_f32_e32 v20, v20, v28
	v_mul_f32_e32 v28, v16, v20
	v_mul_f32_e32 v16, 0xbfb8aa3b, v21
	v_exp_f32_e32 v16, v16
	s_nop 0
	v_add_f32_e32 v16, 1.0, v16
	v_rcp_f32_e32 v16, v16
	s_nop 0
	v_mul_f32_e32 v16, v21, v16
	v_mul_f32_e32 v29, v17, v16
	v_mul_f32_e32 v16, 0xbfb8aa3b, v22
	v_exp_f32_e32 v16, v16
	v_lshl_add_u64 v[20:21], v[32:33], 0, v[112:113]
	v_cvt_pk_bf16_f32 v17, v26, v27
	v_add_f32_e32 v16, 1.0, v16
	v_rcp_f32_e32 v16, v16
	s_nop 0
	v_mul_f32_e32 v16, v22, v16
	v_mul_f32_e32 v22, v18, v16
	v_mul_f32_e32 v16, 0xbfb8aa3b, v23
	v_exp_f32_e32 v16, v16
	v_cvt_pk_bf16_f32 v18, v28, v29
	s_nop 0
	v_add_f32_e32 v16, 1.0, v16
	v_rcp_f32_e32 v16, v16
	s_nop 0
	v_mul_f32_e32 v16, v23, v16
	v_mul_f32_e32 v19, v19, v16
	v_cvt_pk_bf16_f32 v16, v24, v25
	v_cvt_pk_bf16_f32 v19, v22, v19
	global_store_dwordx4 v[20:21], v[16:19], off
	s_nop 1
	v_mul_f32_e32 v18, 0xbfb8aa3b, v12
	v_exp_f32_e32 v18, v18
	v_add_u32_e32 v16, 0xb0, v144
	v_mad_i64_i32 v[16:17], s[16:17], v16, s7, v[138:139]
	v_add_f32_e32 v18, 1.0, v18
	v_rcp_f32_e32 v18, v18
	s_mov_b64 s[16:17], s[12:13]
	v_mul_f32_e32 v12, v12, v18
	v_mul_f32_e32 v8, v8, v12
	v_mul_f32_e32 v12, 0xbfb8aa3b, v13
	v_exp_f32_e32 v12, v12
	s_nop 0
	v_add_f32_e32 v12, 1.0, v12
	v_rcp_f32_e32 v12, v12
	s_nop 0
	v_mul_f32_e32 v12, v13, v12
	v_mul_f32_e32 v9, v9, v12
	v_mul_f32_e32 v12, 0xbfb8aa3b, v14
	v_exp_f32_e32 v12, v12
	s_nop 0
	v_add_f32_e32 v12, 1.0, v12
	v_rcp_f32_e32 v12, v12
	s_nop 0
	v_mul_f32_e32 v12, v14, v12
	v_mul_f32_e32 v10, v10, v12
	v_mul_f32_e32 v12, 0xbfb8aa3b, v15
	v_exp_f32_e32 v12, v12
	s_nop 0
	v_add_f32_e32 v12, 1.0, v12
	v_rcp_f32_e32 v12, v12
	s_nop 0
	v_mul_f32_e32 v12, v15, v12
	v_mul_f32_e32 v11, v11, v12
	v_mul_f32_e32 v12, 0xbfb8aa3b, v4
	v_exp_f32_e32 v12, v12
	s_nop 0
	v_add_f32_e32 v12, 1.0, v12
	v_rcp_f32_e32 v12, v12
	s_nop 0
	v_mul_f32_e32 v4, v4, v12
	v_mul_f32_e32 v12, v0, v4
	v_mul_f32_e32 v0, 0xbfb8aa3b, v5
	v_exp_f32_e32 v0, v0
	s_nop 0
	v_add_f32_e32 v0, 1.0, v0
	v_rcp_f32_e32 v0, v0
	s_nop 0
	v_mul_f32_e32 v0, v5, v0
	v_mul_f32_e32 v13, v1, v0
	v_mul_f32_e32 v0, 0xbfb8aa3b, v6
	v_exp_f32_e32 v0, v0
	v_lshl_add_u64 v[4:5], v[16:17], 0, v[112:113]
	v_cvt_pk_bf16_f32 v1, v10, v11
	v_add_f32_e32 v0, 1.0, v0
	v_rcp_f32_e32 v0, v0
	s_nop 0
	v_mul_f32_e32 v0, v6, v0
	v_mul_f32_e32 v6, v2, v0
	v_mul_f32_e32 v0, 0xbfb8aa3b, v7
	v_exp_f32_e32 v0, v0
	v_cvt_pk_bf16_f32 v2, v12, v13
	s_nop 0
	v_add_f32_e32 v0, 1.0, v0
	v_rcp_f32_e32 v0, v0
	s_nop 0
	v_mul_f32_e32 v0, v7, v0
	v_mul_f32_e32 v3, v3, v0
	v_cvt_pk_bf16_f32 v0, v8, v9
	v_cvt_pk_bf16_f32 v3, v6, v3
	global_store_dwordx4 v[4:5], v[0:3], off
	s_cbranch_vccz .LBB0_210
	s_waitcnt vmcnt(0)
	s_cmpk_gt_u32 s24, 0xff
	s_cbranch_scc1 .LBB0_217
	s_barrier

; #define PG8_STAGE(bufoff, gbase, voff) do { _Pragma("unroll") for (int _i = 0; _i < 2; ++_i) \
;         __builtin_amdgcn_global_load_lds((const unsigned*)((const char*)(gbase) + (voff)[_i]), (LAS unsigned*)(lds + (bufoff) + ldsw + _i * 8192), 16, 0, 0); } while (0)
; #define PG8_LDA(dst, b, h) do { _Pragma("unroll") for (int m = 0; m < 4; ++m) _Pragma("unroll") for (int k = 0; k < 2; ++k) dst[m][k] = *(const LAS bf16x8*)(lds + PG8_SA(b, h) + aoff + m * 2048 + k * 1024); } while (0)
; #define PG8_LDB(dst, b, h) do { _Pragma("unroll") for (int n = 0; n < 2; ++n) _Pragma("unroll") for (int k = 0; k < 2; ++k) dst[n][k] = *(const LAS bf16x8*)(lds + PG8_SB(b, h) + boff + n * 2048 + k * 1024); } while (0)
; #define PG8_MMA(ai, bj, At, Bt) do { __builtin_amdgcn_s_setprio(1); _Pragma("unroll") for (int m = 0; m < 4; ++m) _Pragma("unroll") for (int n = 0; n < 2; ++n) _Pragma("unroll") for (int k = 0; k < 2; ++k) \
;         acc[ai][bj][m][n] = __builtin_amdgcn_mfma_f32_16x16x32_bf16(Bt[n][k], At[m][k], acc[ai][bj][m][n], 0, 0, 0); __builtin_amdgcn_s_setprio(0); } while (0)
; #define PG8_WAIT_V(n) asm volatile("s_waitcnt vmcnt(" #n ")" ::: "memory")
; #define PG8_WAIT_L(n) asm volatile("s_waitcnt lgkmcnt(" #n ")" ::: "memory")
; #define PG8_BAR __builtin_amdgcn_s_barrier()
; template <class Epi, class Sched>
; __device__ __forceinline__ void gemm_phase(LAS unsigned char* lds, const Gemm g, const Sched& S, const Epi& E) {
;     ...
;             const bool last = (t == nt - 2);
;             const char* a1 = cA + (size_t)(t + 1) * kstep;
;             const char* a2 = last ? nA : cA + (size_t)(t + 2) * kstep; const char* b2 = last ? nB : cB + (size_t)(t + 2) * kstep;
;             const char* a3 = a2 + kstep; const char* b3 = b2 + kstep;
;             PG8_LDB(B0, 0, 0); PG8_SCHED; PG8_LDA(At, 0, 0); PG8_STAGE(PG8_SA(1, 1), a1 + hstep, voffA);
;             PG8_WAIT_L(8); PG8_BAR; PG8_WAIT_L(0); PG8_MMA(0, 0, At, B0); PG8_BAR; PG8_SCHED;
;             PG8_LDB(B1, 0, 1); PG8_STAGE(PG8_SB(0, 0), b2, voffB);
;             PG8_BAR; PG8_WAIT_L(0); PG8_MMA(0, 1, At, B1); PG8_BAR;
;             PG8_LDA(At, 0, 1); PG8_STAGE(PG8_SA(0, 0), a2, voffA);
;             PG8_BAR; PG8_WAIT_L(0); PG8_MMA(1, 0, At, B0); PG8_BAR; PG8_SCHED;
;             PG8_STAGE(PG8_SB(0, 1), b2 + hstep, voffB);
;             PG8_WAIT_V(6); PG8_BAR; PG8_MMA(1, 1, At, B1); PG8_BAR;
.LBB0_267:
	s_add_i32 s47, s22, 2
	s_add_u32 s20, s16, 0x100
	s_addc_u32 s21, s17, 0
	s_add_i32 s48, 0, 0x10000
	ds_read_b128 v[128:131], v161
	ds_read_b128 v[132:135], v161 offset:1024
	ds_read_b128 v[136:139], v161 offset:2048
	ds_read_b128 v[140:143], v161 offset:3072
	s_cmp_eq_u32 s11, s22
	s_cselect_b32 s22, s4, s13
	s_cselect_b32 s25, s7, s21
	s_cselect_b32 s24, s6, s20
	s_cselect_b32 s23, s5, s15
	s_add_i32 m0, s33, 0xc000
	ds_read_b128 v[144:147], v203
	ds_read_b128 v[166:169], v203 offset:1024
	ds_read_b128 v[170:173], v203 offset:2048
	ds_read_b128 v[174:177], v203 offset:3072
	ds_read_b128 v[204:207], v203 offset:4096
	ds_read_b128 v[208:211], v203 offset:5120
	ds_read_b128 v[212:215], v203 offset:6144
	ds_read_b128 v[216:219], v203 offset:7168
	global_load_lds_dwordx4 v162, s[16:17]
	s_add_i32 m0, s33, 0xe000
	s_nop 0
	global_load_lds_dwordx4 v164, s[16:17]
	s_waitcnt lgkmcnt(8)
	s_barrier
	s_waitcnt lgkmcnt(7)
	v_mfma_f32_16x16x32_bf16 v[124:127], v[128:131], v[144:147], v[124:127]
	v_mfma_f32_16x16x32_bf16 v[120:123], v[136:139], v[144:147], v[120:123]
	s_waitcnt lgkmcnt(5)
	v_mfma_f32_16x16x32_bf16 v[116:119], v[128:131], v[170:173], v[116:119]
	v_mfma_f32_16x16x32_bf16 v[112:115], v[136:139], v[170:173], v[112:115]
	s_waitcnt lgkmcnt(3)
	v_mfma_f32_16x16x32_bf16 v[100:103], v[128:131], v[204:207], v[100:103]
	v_mfma_f32_16x16x32_bf16 v[96:99], v[136:139], v[204:207], v[96:99]
	s_waitcnt lgkmcnt(1)
	v_mfma_f32_16x16x32_bf16 v[84:87], v[128:131], v[212:215], v[84:87]
	v_mfma_f32_16x16x32_bf16 v[80:83], v[136:139], v[212:215], v[80:83]
	v_mfma_f32_16x16x32_bf16 v[124:127], v[132:135], v[166:169], v[124:127]
	v_mfma_f32_16x16x32_bf16 v[120:123], v[140:143], v[166:169], v[120:123]
	v_mfma_f32_16x16x32_bf16 v[116:119], v[132:135], v[174:177], v[116:119]
	v_mfma_f32_16x16x32_bf16 v[112:115], v[140:143], v[174:177], v[112:115]
	v_mfma_f32_16x16x32_bf16 v[100:103], v[132:135], v[208:211], v[100:103]
	v_mfma_f32_16x16x32_bf16 v[96:99], v[140:143], v[208:211], v[96:99]
	s_waitcnt lgkmcnt(0)
	v_mfma_f32_16x16x32_bf16 v[84:87], v[132:135], v[216:219], v[84:87]
	v_mfma_f32_16x16x32_bf16 v[80:83], v[140:143], v[216:219], v[80:83]
	s_barrier
	s_add_i32 s49, 0, 0x14000
	s_add_i32 s16, s48, s31
	ds_read_b128 v[220:223], v161 offset:16384
	ds_read_b128 v[224:227], v161 offset:17408
	ds_read_b128 v[228:231], v161 offset:18432
	ds_read_b128 v[232:235], v161 offset:19456
	s_add_u32 s84, s22, 0x80
	s_addc_u32 s85, s23, 0
	s_mov_b32 m0, s16
	s_nop 0
	global_load_lds_dwordx4 v148, s[22:23]
	s_add_i32 m0, s16, 0x2000
	s_nop 0
	global_load_lds_dwordx4 v160, s[22:23]
	s_barrier
	s_waitcnt lgkmcnt(0)
	v_mfma_f32_16x16x32_bf16 v[108:111], v[220:223], v[144:147], v[108:111]
	v_mfma_f32_16x16x32_bf16 v[104:107], v[228:231], v[144:147], v[104:107]
	v_mfma_f32_16x16x32_bf16 v[92:95], v[220:223], v[170:173], v[92:95]
	v_mfma_f32_16x16x32_bf16 v[88:91], v[228:231], v[170:173], v[88:91]
	v_mfma_f32_16x16x32_bf16 v[76:79], v[220:223], v[204:207], v[76:79]
	v_mfma_f32_16x16x32_bf16 v[72:75], v[228:231], v[204:207], v[72:75]
	v_mfma_f32_16x16x32_bf16 v[68:71], v[220:223], v[212:215], v[68:71]
	v_mfma_f32_16x16x32_bf16 v[64:67], v[228:231], v[212:215], v[64:67]
	v_mfma_f32_16x16x32_bf16 v[108:111], v[224:227], v[166:169], v[108:111]
	v_mfma_f32_16x16x32_bf16 v[104:107], v[232:235], v[166:169], v[104:107]
	v_mfma_f32_16x16x32_bf16 v[92:95], v[224:227], v[174:177], v[92:95]
	v_mfma_f32_16x16x32_bf16 v[88:91], v[232:235], v[174:177], v[88:91]
	v_mfma_f32_16x16x32_bf16 v[76:79], v[224:227], v[208:211], v[76:79]
	v_mfma_f32_16x16x32_bf16 v[72:75], v[232:235], v[208:211], v[72:75]
	v_mfma_f32_16x16x32_bf16 v[68:71], v[224:227], v[216:219], v[68:71]
	v_mfma_f32_16x16x32_bf16 v[64:67], v[232:235], v[216:219], v[64:67]
	s_barrier
	s_mov_b32 m0, s33
	s_add_u32 s86, s24, 0x80
	s_addc_u32 s87, s25, 0
	ds_read_b128 v[144:147], v203 offset:16384
	ds_read_b128 v[166:169], v203 offset:17408
	ds_read_b128 v[170:173], v203 offset:18432
	ds_read_b128 v[174:177], v203 offset:19456
	ds_read_b128 v[204:207], v203 offset:20480
	ds_read_b128 v[208:211], v203 offset:21504
	ds_read_b128 v[212:215], v203 offset:22528
	ds_read_b128 v[216:219], v203 offset:23552
	global_load_lds_dwordx4 v148, s[24:25]
	s_mov_b32 m0, s34
	s_nop 0
	global_load_lds_dwordx4 v160, s[24:25]
	s_barrier
	s_waitcnt lgkmcnt(0)
	v_mfma_f32_16x16x32_bf16 v[60:63], v[128:131], v[144:147], v[60:63]
	v_mfma_f32_16x16x32_bf16 v[56:59], v[136:139], v[144:147], v[56:59]
	v_mfma_f32_16x16x32_bf16 v[52:55], v[128:131], v[170:173], v[52:55]
	v_mfma_f32_16x16x32_bf16 v[48:51], v[136:139], v[170:173], v[48:51]
	v_mfma_f32_16x16x32_bf16 v[36:39], v[128:131], v[204:207], v[36:39]
	v_mfma_f32_16x16x32_bf16 v[32:35], v[136:139], v[204:207], v[32:35]
	v_mfma_f32_16x16x32_bf16 v[20:23], v[128:131], v[212:215], v[20:23]
	v_mfma_f32_16x16x32_bf16 v[16:19], v[136:139], v[212:215], v[16:19]
	v_mfma_f32_16x16x32_bf16 v[60:63], v[132:135], v[166:169], v[60:63]
	v_mfma_f32_16x16x32_bf16 v[56:59], v[140:143], v[166:169], v[56:59]
	v_mfma_f32_16x16x32_bf16 v[52:55], v[132:135], v[174:177], v[52:55]
	v_mfma_f32_16x16x32_bf16 v[48:51], v[140:143], v[174:177], v[48:51]
	v_mfma_f32_16x16x32_bf16 v[36:39], v[132:135], v[208:211], v[36:39]
	v_mfma_f32_16x16x32_bf16 v[32:35], v[140:143], v[208:211], v[32:35]
	v_mfma_f32_16x16x32_bf16 v[20:23], v[132:135], v[216:219], v[20:23]
	v_mfma_f32_16x16x32_bf16 v[16:19], v[140:143], v[216:219], v[16:19]
	s_barrier
	s_add_u32 s16, s22, 0x80000
	s_addc_u32 s17, s23, 0
	s_add_i32 s48, s49, s31
	s_mov_b32 m0, s48
	s_nop 0
	global_load_lds_dwordx4 v148, s[16:17]
	s_add_i32 m0, s48, 0x2000
	s_nop 0
	global_load_lds_dwordx4 v160, s[16:17]
	s_waitcnt vmcnt(6)
	s_barrier
; #define PG8_STAGE(bufoff, gbase, voff) do { _Pragma("unroll") for (int _i = 0; _i < 2; ++_i) \
;         __builtin_amdgcn_global_load_lds((const unsigned*)((const char*)(gbase) + (voff)[_i]), (LAS unsigned*)(lds + (bufoff) + ldsw + _i * 8192), 16, 0, 0); } while (0)
; #define PG8_LDA(dst, b, h) do { _Pragma("unroll") for (int m = 0; m < 4; ++m) _Pragma("unroll") for (int k = 0; k < 2; ++k) dst[m][k] = *(const LAS bf16x8*)(lds + PG8_SA(b, h) + aoff + m * 2048 + k * 1024); } while (0)
; #define PG8_LDB(dst, b, h) do { _Pragma("unroll") for (int n = 0; n < 2; ++n) _Pragma("unroll") for (int k = 0; k < 2; ++k) dst[n][k] = *(const LAS bf16x8*)(lds + PG8_SB(b, h) + boff + n * 2048 + k * 1024); } while (0)
; #define PG8_MMA(ai, bj, At, Bt) do { __builtin_amdgcn_s_setprio(1); _Pragma("unroll") for (int m = 0; m < 4; ++m) _Pragma("unroll") for (int n = 0; n < 2; ++n) _Pragma("unroll") for (int k = 0; k < 2; ++k) \
;         acc[ai][bj][m][n] = __builtin_amdgcn_mfma_f32_16x16x32_bf16(Bt[n][k], At[m][k], acc[ai][bj][m][n], 0, 0, 0); __builtin_amdgcn_s_setprio(0); } while (0)
; #define PG8_WAIT_V(n) asm volatile("s_waitcnt vmcnt(" #n ")" ::: "memory")
; #define PG8_WAIT_L(n) asm volatile("s_waitcnt lgkmcnt(" #n ")" ::: "memory")
; #define PG8_BAR __builtin_amdgcn_s_barrier()
; #define PG8_SCHED __builtin_amdgcn_sched_barrier(0)
; template <class Epi, class Sched>
; __device__ __forceinline__ void gemm_phase(LAS unsigned char* lds, const Gemm g, const Sched& S, const Epi& E) {
;     ...
;             PG8_WAIT_V(6); PG8_BAR; PG8_MMA(1, 1, At, B1); PG8_BAR;
;             PG8_LDB(B0, 1, 0); PG8_SCHED; PG8_LDA(At, 1, 0); PG8_STAGE(PG8_SA(0, 1), a2 + hstep, voffA);
;             PG8_WAIT_L(8); PG8_BAR; PG8_WAIT_L(0); PG8_MMA(0, 0, At, B0); PG8_BAR; PG8_SCHED;
;             PG8_LDB(B1, 1, 1); PG8_STAGE(PG8_SB(1, 0), b3, voffB);
;             PG8_BAR; PG8_WAIT_L(0); PG8_MMA(0, 1, At, B1); PG8_BAR;
;             PG8_LDA(At, 1, 1); PG8_STAGE(PG8_SA(1, 0), a3, voffA);
;             PG8_BAR; PG8_WAIT_L(0); PG8_MMA(1, 0, At, B0); PG8_BAR; PG8_SCHED;
	v_mfma_f32_16x16x32_bf16 v[44:47], v[220:223], v[144:147], v[44:47]
	v_mfma_f32_16x16x32_bf16 v[40:43], v[228:231], v[144:147], v[40:43]
	v_mfma_f32_16x16x32_bf16 v[28:31], v[220:223], v[170:173], v[28:31]
	v_mfma_f32_16x16x32_bf16 v[24:27], v[228:231], v[170:173], v[24:27]
	v_mfma_f32_16x16x32_bf16 v[12:15], v[220:223], v[204:207], v[12:15]
	v_mfma_f32_16x16x32_bf16 v[8:11], v[228:231], v[204:207], v[8:11]
	v_mfma_f32_16x16x32_bf16 v[4:7], v[220:223], v[212:215], v[4:7]
	v_mfma_f32_16x16x32_bf16 v[0:3], v[228:231], v[212:215], v[0:3]
	v_mfma_f32_16x16x32_bf16 v[44:47], v[224:227], v[166:169], v[44:47]
	v_mfma_f32_16x16x32_bf16 v[40:43], v[232:235], v[166:169], v[40:43]
	v_mfma_f32_16x16x32_bf16 v[28:31], v[224:227], v[174:177], v[28:31]
	v_mfma_f32_16x16x32_bf16 v[24:27], v[232:235], v[174:177], v[24:27]
	v_mfma_f32_16x16x32_bf16 v[12:15], v[224:227], v[208:211], v[12:15]
	v_mfma_f32_16x16x32_bf16 v[8:11], v[232:235], v[208:211], v[8:11]
	v_mfma_f32_16x16x32_bf16 v[4:7], v[224:227], v[216:219], v[4:7]
	v_mfma_f32_16x16x32_bf16 v[0:3], v[232:235], v[216:219], v[0:3]
	s_barrier
	s_add_i32 s48, 0, 0x18000
	ds_read_b128 v[128:131], v161 offset:32768
	ds_read_b128 v[132:135], v161 offset:33792
	ds_read_b128 v[136:139], v161 offset:34816
	ds_read_b128 v[140:143], v161 offset:35840
	s_add_u32 s16, s24, 0x80000
	s_addc_u32 s17, s25, 0
	s_mov_b32 m0, s35
	ds_read_b128 v[144:147], v203 offset:32768
	ds_read_b128 v[166:169], v203 offset:33792
	ds_read_b128 v[170:173], v203 offset:34816
	ds_read_b128 v[174:177], v203 offset:35840
	ds_read_b128 v[204:207], v203 offset:36864
	ds_read_b128 v[208:211], v203 offset:37888
	ds_read_b128 v[212:215], v203 offset:38912
	ds_read_b128 v[216:219], v203 offset:39936
	global_load_lds_dwordx4 v148, s[16:17]
	s_mov_b32 m0, s36
	s_nop 0
	global_load_lds_dwordx4 v160, s[16:17]
	s_waitcnt lgkmcnt(8)
	s_barrier
	s_waitcnt lgkmcnt(7)
	v_mfma_f32_16x16x32_bf16 v[124:127], v[128:131], v[144:147], v[124:127]
	v_mfma_f32_16x16x32_bf16 v[120:123], v[136:139], v[144:147], v[120:123]
	s_waitcnt lgkmcnt(5)
	v_mfma_f32_16x16x32_bf16 v[116:119], v[128:131], v[170:173], v[116:119]
	v_mfma_f32_16x16x32_bf16 v[112:115], v[136:139], v[170:173], v[112:115]
	s_waitcnt lgkmcnt(3)
	v_mfma_f32_16x16x32_bf16 v[100:103], v[128:131], v[204:207], v[100:103]
	v_mfma_f32_16x16x32_bf16 v[96:99], v[136:139], v[204:207], v[96:99]
	s_waitcnt lgkmcnt(1)
	v_mfma_f32_16x16x32_bf16 v[84:87], v[128:131], v[212:215], v[84:87]
	v_mfma_f32_16x16x32_bf16 v[80:83], v[136:139], v[212:215], v[80:83]
	v_mfma_f32_16x16x32_bf16 v[124:127], v[132:135], v[166:169], v[124:127]
	v_mfma_f32_16x16x32_bf16 v[120:123], v[140:143], v[166:169], v[120:123]
	v_mfma_f32_16x16x32_bf16 v[116:119], v[132:135], v[174:177], v[116:119]
	v_mfma_f32_16x16x32_bf16 v[112:115], v[140:143], v[174:177], v[112:115]
	v_mfma_f32_16x16x32_bf16 v[100:103], v[132:135], v[208:211], v[100:103]
	v_mfma_f32_16x16x32_bf16 v[96:99], v[140:143], v[208:211], v[96:99]
	s_waitcnt lgkmcnt(0)
	v_mfma_f32_16x16x32_bf16 v[84:87], v[132:135], v[216:219], v[84:87]
	v_mfma_f32_16x16x32_bf16 v[80:83], v[140:143], v[216:219], v[80:83]
	s_barrier
	s_add_i32 s24, 0, 0x1c000
	s_add_i32 s16, s48, s31
	s_mov_b32 m0, s16
	ds_read_b128 v[220:223], v161 offset:49152
	ds_read_b128 v[224:227], v161 offset:50176
	ds_read_b128 v[228:231], v161 offset:51200
	ds_read_b128 v[232:235], v161 offset:52224
	global_load_lds_dwordx4 v148, s[84:85]
	s_add_i32 m0, s16, 0x2000
	s_nop 0
	global_load_lds_dwordx4 v160, s[84:85]
	s_barrier
	s_waitcnt lgkmcnt(0)
	v_mfma_f32_16x16x32_bf16 v[108:111], v[220:223], v[144:147], v[108:111]
	v_mfma_f32_16x16x32_bf16 v[104:107], v[228:231], v[144:147], v[104:107]
	v_mfma_f32_16x16x32_bf16 v[92:95], v[220:223], v[170:173], v[92:95]
	v_mfma_f32_16x16x32_bf16 v[88:91], v[228:231], v[170:173], v[88:91]
	v_mfma_f32_16x16x32_bf16 v[76:79], v[220:223], v[204:207], v[76:79]
	v_mfma_f32_16x16x32_bf16 v[72:75], v[228:231], v[204:207], v[72:75]
	v_mfma_f32_16x16x32_bf16 v[68:71], v[220:223], v[212:215], v[68:71]
	v_mfma_f32_16x16x32_bf16 v[64:67], v[228:231], v[212:215], v[64:67]
	v_mfma_f32_16x16x32_bf16 v[108:111], v[224:227], v[166:169], v[108:111]
	v_mfma_f32_16x16x32_bf16 v[104:107], v[232:235], v[166:169], v[104:107]
	v_mfma_f32_16x16x32_bf16 v[92:95], v[224:227], v[174:177], v[92:95]
	v_mfma_f32_16x16x32_bf16 v[88:91], v[232:235], v[174:177], v[88:91]
	v_mfma_f32_16x16x32_bf16 v[76:79], v[224:227], v[208:211], v[76:79]
	v_mfma_f32_16x16x32_bf16 v[72:75], v[232:235], v[208:211], v[72:75]
	v_mfma_f32_16x16x32_bf16 v[68:71], v[224:227], v[216:219], v[68:71]
	v_mfma_f32_16x16x32_bf16 v[64:67], v[232:235], v[216:219], v[64:67]
	s_barrier
	s_mov_b32 m0, s39
	ds_read_b128 v[144:147], v203 offset:49152
	ds_read_b128 v[166:169], v203 offset:50176
	ds_read_b128 v[170:173], v203 offset:51200
	ds_read_b128 v[174:177], v203 offset:52224
	ds_read_b128 v[204:207], v203 offset:53248
	ds_read_b128 v[208:211], v203 offset:54272
	ds_read_b128 v[212:215], v203 offset:55296
	ds_read_b128 v[216:219], v203 offset:56320
	global_load_lds_dwordx4 v148, s[86:87]
	s_mov_b32 m0, s40
	s_nop 0
	global_load_lds_dwordx4 v160, s[86:87]
	s_barrier
; #define PG8_STAGE(bufoff, gbase, voff) do { _Pragma("unroll") for (int _i = 0; _i < 2; ++_i) \
;         __builtin_amdgcn_global_load_lds((const unsigned*)((const char*)(gbase) + (voff)[_i]), (LAS unsigned*)(lds + (bufoff) + ldsw + _i * 8192), 16, 0, 0); } while (0)
; #define PG8_MMA(ai, bj, At, Bt) do { __builtin_amdgcn_s_setprio(1); _Pragma("unroll") for (int m = 0; m < 4; ++m) _Pragma("unroll") for (int n = 0; n < 2; ++n) _Pragma("unroll") for (int k = 0; k < 2; ++k) \
;         acc[ai][bj][m][n] = __builtin_amdgcn_mfma_f32_16x16x32_bf16(Bt[n][k], At[m][k], acc[ai][bj][m][n], 0, 0, 0); __builtin_amdgcn_s_setprio(0); } while (0)
; #define PG8_WAIT_V(n) asm volatile("s_waitcnt vmcnt(" #n ")" ::: "memory")
; #define PG8_WAIT_L(n) asm volatile("s_waitcnt lgkmcnt(" #n ")" ::: "memory")
;     __device__ __forceinline__ void operator()(const f32x4 (&acc)[2][2][4][2], const Unit& u, int wr, int wc, int fr, int fq) const {
;         const int row0 = u.pm * BM + wr * 64 + fr, col0 = u.pn * BM + wc * 32 + 4 * fq;
;         if (u.slice >= 0) {
;             float* pb = P + (size_t)u.slice * 512 * DM;
; #pragma unroll
;             for (int ai = 0; ai < 2; ++ai)
; #pragma unroll
;                 for (int m = 0; m < 4; ++m) { const size_t off = (size_t)(row0 - MP + ai * HALF + m * 16) * DM + col0;
; #pragma unroll
;                     for (int bj = 0; bj < 2; ++bj)
; #pragma unroll
;                         for (int n = 0; n < 2; ++n) *(f32x4*)(pb + off + bj * HALF + n * 16) = acc[ai][bj][m][n]; }
;             return;
;         }
;         const float* base = (u.pm < 32) ? base_lo : base_hi;
; #pragma unroll
;         for (int ai = 0; ai < 2; ++ai) {
;             f32x4 bs[4][2][2];
; #pragma unroll
;             for (int m = 0; m < 4; ++m) { const size_t off = (size_t)(row0 + ai * HALF + m * 16) * DM + col0;
; #pragma unroll
;                 for (int bj = 0; bj < 2; ++bj)
; #pragma unroll
;                     for (int n = 0; n < 2; ++n) bs[m][bj][n] = *(const f32x4*)(base + off + bj * HALF + n * 16); }
; template <class Epi, class Sched>
; __device__ __forceinline__ void gemm_phase(LAS unsigned char* lds, const Gemm g, const Sched& S, const Epi& E) {
;     ...
;             PG8_BAR; PG8_WAIT_L(0); PG8_MMA(1, 0, At, B0); PG8_BAR; PG8_SCHED;
;             PG8_STAGE(PG8_SB(1, 1), b3 + hstep, voffB);
;             PG8_WAIT_V(6); PG8_BAR; PG8_MMA(1, 1, At, B1); PG8_BAR;
	s_waitcnt lgkmcnt(0)
	v_mfma_f32_16x16x32_bf16 v[60:63], v[128:131], v[144:147], v[60:63]
	v_mfma_f32_16x16x32_bf16 v[56:59], v[136:139], v[144:147], v[56:59]
	v_mfma_f32_16x16x32_bf16 v[52:55], v[128:131], v[170:173], v[52:55]
	v_mfma_f32_16x16x32_bf16 v[48:51], v[136:139], v[170:173], v[48:51]
	v_mfma_f32_16x16x32_bf16 v[36:39], v[128:131], v[204:207], v[36:39]
	v_mfma_f32_16x16x32_bf16 v[32:35], v[136:139], v[204:207], v[32:35]
	v_mfma_f32_16x16x32_bf16 v[20:23], v[128:131], v[212:215], v[20:23]
	v_mfma_f32_16x16x32_bf16 v[16:19], v[136:139], v[212:215], v[16:19]
	v_mfma_f32_16x16x32_bf16 v[60:63], v[132:135], v[166:169], v[60:63]
	v_mfma_f32_16x16x32_bf16 v[56:59], v[140:143], v[166:169], v[56:59]
	v_mfma_f32_16x16x32_bf16 v[52:55], v[132:135], v[174:177], v[52:55]
	v_mfma_f32_16x16x32_bf16 v[48:51], v[140:143], v[174:177], v[48:51]
	v_mfma_f32_16x16x32_bf16 v[36:39], v[132:135], v[208:211], v[36:39]
	v_mfma_f32_16x16x32_bf16 v[32:35], v[140:143], v[208:211], v[32:35]
	v_mfma_f32_16x16x32_bf16 v[20:23], v[132:135], v[216:219], v[20:23]
	v_mfma_f32_16x16x32_bf16 v[16:19], v[140:143], v[216:219], v[16:19]
	s_barrier
	s_add_u32 s16, s22, 0x80080
	s_addc_u32 s17, s23, 0
	s_add_i32 s22, s24, s31
	s_mov_b32 m0, s22
	s_nop 0
	global_load_lds_dwordx4 v148, s[16:17]
	s_add_i32 m0, s22, 0x2000
	s_nop 0
	global_load_lds_dwordx4 v160, s[16:17]
	s_add_u32 s13, s13, 0x100
	s_addc_u32 s15, s15, 0
	s_cmp_ge_i32 s47, s45
	s_mov_b64 s[16:17], s[20:21]
	s_mov_b32 s22, s47
	s_waitcnt vmcnt(6)
	s_barrier
	v_mfma_f32_16x16x32_bf16 v[44:47], v[220:223], v[144:147], v[44:47]
	v_mfma_f32_16x16x32_bf16 v[40:43], v[228:231], v[144:147], v[40:43]
	v_mfma_f32_16x16x32_bf16 v[28:31], v[220:223], v[170:173], v[28:31]
	v_mfma_f32_16x16x32_bf16 v[24:27], v[228:231], v[170:173], v[24:27]
	v_mfma_f32_16x16x32_bf16 v[12:15], v[220:223], v[204:207], v[12:15]
	v_mfma_f32_16x16x32_bf16 v[8:11], v[228:231], v[204:207], v[8:11]
	v_mfma_f32_16x16x32_bf16 v[4:7], v[220:223], v[212:215], v[4:7]
	v_mfma_f32_16x16x32_bf16 v[0:3], v[228:231], v[212:215], v[0:3]
	v_mfma_f32_16x16x32_bf16 v[44:47], v[224:227], v[166:169], v[44:47]
	v_mfma_f32_16x16x32_bf16 v[40:43], v[232:235], v[166:169], v[40:43]
	v_mfma_f32_16x16x32_bf16 v[28:31], v[224:227], v[174:177], v[28:31]
	v_mfma_f32_16x16x32_bf16 v[24:27], v[232:235], v[174:177], v[24:27]
	v_mfma_f32_16x16x32_bf16 v[12:15], v[224:227], v[208:211], v[12:15]
	v_mfma_f32_16x16x32_bf16 v[8:11], v[232:235], v[208:211], v[8:11]
	v_mfma_f32_16x16x32_bf16 v[4:7], v[224:227], v[216:219], v[4:7]
	v_mfma_f32_16x16x32_bf16 v[0:3], v[232:235], v[216:219], v[0:3]
	s_barrier
	s_cbranch_scc0 .LBB0_267
	v_lshl_add_u32 v166, s46, 8, v200
	v_lshl_or_b32 v168, s44, 8, v202
	s_mov_b64 s[16:17], -1
	s_cmp_lt_i32 s82, 0
	v_ashrrev_i32_e32 v169, 31, v168
	v_ashrrev_i32_e32 v167, 31, v166
	s_cbranch_scc0 .LBB0_270
	v_lshlrev_b64 v[170:171], 2, v[168:169]
	v_lshl_add_u64 v[172:173], s[60:61], 0, v[170:171]
	v_lshlrev_b64 v[174:175], 13, v[166:167]
	v_lshl_add_u64 v[128:129], v[172:173], 0, v[174:175]
	global_load_dwordx4 v[204:207], v[128:129], off
	global_load_dwordx4 v[208:211], v[128:129], off offset:64
	global_load_dwordx4 v[212:215], v[128:129], off offset:512
	global_load_dwordx4 v[216:219], v[128:129], off offset:576
	v_or_b32_e32 v128, 16, v166
	v_ashrrev_i32_e32 v129, 31, v128
	v_lshlrev_b64 v[188:189], 13, v[128:129]
	v_lshl_add_u64 v[128:129], v[172:173], 0, v[188:189]
	global_load_dwordx4 v[220:223], v[128:129], off
	global_load_dwordx4 v[224:227], v[128:129], off offset:64
	global_load_dwordx4 v[228:231], v[128:129], off offset:512
	global_load_dwordx4 v[232:235], v[128:129], off offset:576
	v_or_b32_e32 v128, 32, v166
	v_ashrrev_i32_e32 v129, 31, v128
	v_lshlrev_b64 v[190:191], 13, v[128:129]
	v_lshl_add_u64 v[128:129], v[172:173], 0, v[190:191]
	global_load_dwordx4 v[236:239], v[128:129], off
	global_load_dwordx4 v[240:243], v[128:129], off offset:64
	global_load_dwordx4 v[144:147], v[128:129], off offset:512
	global_load_dwordx4 v[140:143], v[128:129], off offset:576
	v_or_b32_e32 v128, 48, v166
	v_ashrrev_i32_e32 v129, 31, v128
	v_lshlrev_b64 v[176:177], 13, v[128:129]
	v_lshl_add_u64 v[128:129], v[172:173], 0, v[176:177]
	global_load_dwordx4 v[244:247], v[128:129], off
	global_load_dwordx4 v[136:139], v[128:129], off offset:64
	global_load_dwordx4 v[132:135], v[128:129], off offset:512
	s_nop 0
	global_load_dwordx4 v[128:131], v[128:129], off offset:576
	v_lshl_add_u64 v[248:249], s[60:61], 0, v[174:175]
	v_lshl_add_u64 v[248:249], v[248:249], 0, v[170:171]
	v_lshl_add_u64 v[188:189], s[60:61], 0, v[188:189]
	v_lshl_add_u64 v[188:189], v[188:189], 0, v[170:171]
	s_mov_b64 s[16:17], 0x100000
	s_waitcnt vmcnt(0)
;     __device__ __forceinline__ void operator()(const f32x4 (&acc)[2][2][4][2], const Unit& u, int wr, int wc, int fr, int fq) const {
;     ...
;             for (int m = 0; m < 4; ++m) { const size_t off = (size_t)(row0 + ai * HALF + m * 16) * DM + col0;
; #pragma unroll
;                 for (int bj = 0; bj < 2; ++bj)
; #pragma unroll
;                     for (int n = 0; n < 2; ++n) bs[m][bj][n] = *(const f32x4*)(base + off + bj * HALF + n * 16); }
;     ...
;             for (int m = 0; m < 4; ++m) { const size_t off = (size_t)(row0 + ai * HALF + m * 16) * DM + col0;
; #pragma unroll
;                 for (int bj = 0; bj < 2; ++bj)
; #pragma unroll
;                     for (int n = 0; n < 2; ++n) *(f32x4*)(out + off + bj * HALF + n * 16) = bs[m][bj][n] + scale * acc[ai][bj][m][n]; }
	v_pk_add_f32 v[206:207], v[206:207], v[126:127]
	v_pk_add_f32 v[204:205], v[204:205], v[124:125]
	global_store_dwordx4 v[248:249], v[204:207], off
	v_pk_add_f32 v[146:147], v[146:147], v[78:79]
	s_nop 0
	v_pk_add_f32 v[206:207], v[210:211], v[122:123]
	v_pk_add_f32 v[204:205], v[208:209], v[120:121]
	global_store_dwordx4 v[248:249], v[204:207], off offset:64
	v_pk_add_f32 v[144:145], v[144:145], v[76:77]
	v_pk_add_f32 v[142:143], v[142:143], v[74:75]
	v_pk_add_f32 v[206:207], v[214:215], v[110:111]
	v_pk_add_f32 v[204:205], v[212:213], v[108:109]
	global_store_dwordx4 v[248:249], v[204:207], off offset:512
	v_pk_add_f32 v[140:141], v[140:141], v[72:73]
	v_pk_add_f32 v[138:139], v[138:139], v[82:83]
	v_pk_add_f32 v[206:207], v[218:219], v[106:107]
	v_pk_add_f32 v[204:205], v[216:217], v[104:105]
	global_store_dwordx4 v[248:249], v[204:207], off offset:576
	v_pk_add_f32 v[136:137], v[136:137], v[80:81]
	v_pk_add_f32 v[134:135], v[134:135], v[70:71]
	v_pk_add_f32 v[206:207], v[222:223], v[118:119]
	v_pk_add_f32 v[204:205], v[220:221], v[116:117]
	global_store_dwordx4 v[188:189], v[204:207], off
	v_pk_add_f32 v[132:133], v[132:133], v[68:69]
	v_pk_add_f32 v[130:131], v[130:131], v[66:67]
	v_pk_add_f32 v[206:207], v[226:227], v[114:115]
	v_pk_add_f32 v[204:205], v[224:225], v[112:113]
	global_store_dwordx4 v[188:189], v[204:207], off offset:64
	v_pk_add_f32 v[128:129], v[128:129], v[64:65]
	s_nop 0
	v_pk_add_f32 v[206:207], v[230:231], v[94:95]
	v_pk_add_f32 v[204:205], v[228:229], v[92:93]
	global_store_dwordx4 v[188:189], v[204:207], off offset:512
	s_nop 1
	v_pk_add_f32 v[206:207], v[234:235], v[90:91]
	v_pk_add_f32 v[204:205], v[232:233], v[88:89]
	global_store_dwordx4 v[188:189], v[204:207], off offset:576
	v_lshl_add_u64 v[188:189], s[60:61], 0, v[190:191]
	v_lshl_add_u64 v[188:189], v[188:189], 0, v[170:171]
	v_pk_add_f32 v[206:207], v[238:239], v[102:103]
	v_pk_add_f32 v[204:205], v[236:237], v[100:101]
	global_store_dwordx4 v[188:189], v[144:147], off offset:512
	global_store_dwordx4 v[188:189], v[204:207], off
	global_store_dwordx4 v[188:189], v[140:143], off offset:576
	v_lshl_add_u64 v[144:145], s[60:61], 0, v[176:177]
	v_pk_add_f32 v[206:207], v[242:243], v[98:99]
	v_pk_add_f32 v[204:205], v[240:241], v[96:97]
	v_pk_add_f32 v[142:143], v[246:247], v[86:87]
	v_pk_add_f32 v[140:141], v[244:245], v[84:85]
	v_lshl_add_u64 v[144:145], v[144:145], 0, v[170:171]
	global_store_dwordx4 v[188:189], v[204:207], off offset:64
	global_store_dwordx4 v[144:145], v[140:143], off
	global_store_dwordx4 v[144:145], v[136:139], off offset:64
	global_store_dwordx4 v[144:145], v[132:135], off offset:512
	global_store_dwordx4 v[144:145], v[128:131], off offset:576
	v_lshl_add_u64 v[146:147], v[174:175], 0, s[16:17]
	s_mov_b64 s[16:17], 0x120000
	v_lshl_add_u64 v[128:129], v[172:173], 0, v[146:147]
	global_load_dwordx4 v[142:145], v[128:129], off
	global_load_dwordx4 v[204:207], v[128:129], off offset:64
	global_load_dwordx4 v[208:211], v[128:129], off offset:512
	global_load_dwordx4 v[212:215], v[128:129], off offset:576
	v_lshl_add_u64 v[176:177], v[174:175], 0, s[16:17]
	v_lshl_add_u64 v[128:129], v[172:173], 0, v[176:177]
	global_load_dwordx4 v[216:219], v[128:129], off
	global_load_dwordx4 v[220:223], v[128:129], off offset:64
	global_load_dwordx4 v[224:227], v[128:129], off offset:512
	global_load_dwordx4 v[228:231], v[128:129], off offset:576
	s_mov_b64 s[16:17], 0x140000
	v_lshl_add_u64 v[188:189], v[174:175], 0, s[16:17]
	s_mov_b64 s[16:17], 0x160000
	v_lshl_add_u64 v[128:129], v[172:173], 0, v[188:189]
	v_lshl_add_u64 v[140:141], v[174:175], 0, s[16:17]
	global_load_dwordx4 v[232:235], v[128:129], off
	global_load_dwordx4 v[236:239], v[128:129], off offset:64
	global_load_dwordx4 v[240:243], v[128:129], off offset:512
	global_load_dwordx4 v[244:247], v[128:129], off offset:576
	v_lshl_add_u64 v[128:129], v[172:173], 0, v[140:141]
	global_load_dwordx4 v[172:175], v[128:129], off
	global_load_dwordx4 v[136:139], v[128:129], off offset:64
	global_load_dwordx4 v[132:135], v[128:129], off offset:512
	s_nop 0
	global_load_dwordx4 v[128:131], v[128:129], off offset:576
	v_lshl_add_u64 v[146:147], s[60:61], 0, v[146:147]
	v_lshl_add_u64 v[146:147], v[146:147], 0, v[170:171]
	v_lshl_add_u64 v[140:141], s[60:61], 0, v[140:141]
	v_lshl_add_u64 v[140:141], v[140:141], 0, v[170:171]
	s_mov_b64 s[16:17], 0
	s_waitcnt vmcnt(0)
;     __device__ __forceinline__ void operator()(const f32x4 (&acc)[2][2][4][2], const Unit& u, int wr, int wc, int fr, int fq) const {
;     ...
;             for (int m = 0; m < 4; ++m) { const size_t off = (size_t)(row0 + ai * HALF + m * 16) * DM + col0;
; #pragma unroll
;                 for (int bj = 0; bj < 2; ++bj)
; #pragma unroll
;                     for (int n = 0; n < 2; ++n) *(f32x4*)(out + off + bj * HALF + n * 16) = bs[m][bj][n] + scale * acc[ai][bj][m][n]; }
	v_pk_add_f32 v[144:145], v[62:63], v[144:145]
	v_pk_add_f32 v[142:143], v[60:61], v[142:143]
	global_store_dwordx4 v[146:147], v[142:145], off
	v_pk_add_f32 v[138:139], v[18:19], v[138:139]
	s_nop 0
	v_pk_add_f32 v[144:145], v[58:59], v[206:207]
	v_pk_add_f32 v[142:143], v[56:57], v[204:205]
	global_store_dwordx4 v[146:147], v[142:145], off offset:64
	v_pk_add_f32 v[136:137], v[16:17], v[136:137]
	v_pk_add_f32 v[134:135], v[6:7], v[134:135]
	v_pk_add_f32 v[144:145], v[46:47], v[210:211]
	v_pk_add_f32 v[142:143], v[44:45], v[208:209]
	global_store_dwordx4 v[146:147], v[142:145], off offset:512
	v_pk_add_f32 v[132:133], v[4:5], v[132:133]
	v_pk_add_f32 v[130:131], v[2:3], v[130:131]
	v_pk_add_f32 v[144:145], v[42:43], v[214:215]
	v_pk_add_f32 v[142:143], v[40:41], v[212:213]
	global_store_dwordx4 v[146:147], v[142:145], off offset:576
	v_lshl_add_u64 v[146:147], s[60:61], 0, v[176:177]
	v_lshl_add_u64 v[146:147], v[146:147], 0, v[170:171]
	v_pk_add_f32 v[144:145], v[54:55], v[218:219]
	v_pk_add_f32 v[142:143], v[52:53], v[216:217]
	global_store_dwordx4 v[146:147], v[142:145], off
	v_pk_add_f32 v[128:129], v[0:1], v[128:129]
	global_store_dwordx4 v[140:141], v[136:139], off offset:64
	v_pk_add_f32 v[144:145], v[50:51], v[222:223]
	v_pk_add_f32 v[142:143], v[48:49], v[220:221]
	global_store_dwordx4 v[146:147], v[142:145], off offset:64
	global_store_dwordx4 v[140:141], v[132:135], off offset:512
	global_store_dwordx4 v[140:141], v[128:131], off offset:576
	v_pk_add_f32 v[144:145], v[30:31], v[226:227]
	v_pk_add_f32 v[142:143], v[28:29], v[224:225]
	global_store_dwordx4 v[146:147], v[142:145], off offset:512
	s_nop 1
	v_pk_add_f32 v[144:145], v[26:27], v[230:231]
	v_pk_add_f32 v[142:143], v[24:25], v[228:229]
	global_store_dwordx4 v[146:147], v[142:145], off offset:576
	v_lshl_add_u64 v[146:147], s[60:61], 0, v[188:189]
	v_lshl_add_u64 v[146:147], v[146:147], 0, v[170:171]
	v_pk_add_f32 v[144:145], v[38:39], v[234:235]
	v_pk_add_f32 v[142:143], v[36:37], v[232:233]
	global_store_dwordx4 v[146:147], v[142:145], off
	s_nop 1
	v_pk_add_f32 v[144:145], v[34:35], v[238:239]
	v_pk_add_f32 v[142:143], v[32:33], v[236:237]
	global_store_dwordx4 v[146:147], v[142:145], off offset:64
	s_nop 1
	v_pk_add_f32 v[144:145], v[14:15], v[242:243]
	v_pk_add_f32 v[142:143], v[12:13], v[240:241]
	global_store_dwordx4 v[146:147], v[142:145], off offset:512
	s_nop 1
	v_pk_add_f32 v[144:145], v[10:11], v[246:247]
	v_pk_add_f32 v[142:143], v[8:9], v[244:245]
	global_store_dwordx4 v[146:147], v[142:145], off offset:576
	s_nop 1
	v_pk_add_f32 v[144:145], v[22:23], v[174:175]
	v_pk_add_f32 v[142:143], v[20:21], v[172:173]
	global_store_dwordx4 v[140:141], v[142:145], off
